# split-K exchange kept inside one XCD (unit j on XCD j&7, no L2 write-back/invalidate), runtime-guarded by XCC id check with baseline fallback
# speedup vs baseline: 1.0010x; 1.0010x over previous
.LBB0_7:
	v_writelane_b32 v242, s4, 11
	s_getreg_b32 s98, hwreg(HW_REG_XCC_ID, 0, 4)
	s_and_b32 s98, s98, 15
	s_and_b32 s99, s2, 7
	s_cmp_eq_u32 s98, s99
	s_cbranch_scc1 .Lxg_ok
	v_mov_b32_e32 v253, 0xa100
	v_mov_b32_e32 v254, 1
	global_store_dword v253, v254, s[70:71]
.Lxg_ok:
	s_load_dwordx16 s[4:19], s[0:1], 0x40
	s_lshr_b32 s1, s3, 6
	s_lshl_b32 s0, s2, 3
	s_add_i32 s56, s1, s0
	s_lshl_b32 s64, s74, 3
	s_waitcnt lgkmcnt(0)
	v_writelane_b32 v242, s4, 12
	v_and_b32_e32 v142, 63, v143
	s_nop 0
	v_writelane_b32 v242, s5, 13
	v_writelane_b32 v242, s6, 14
	v_writelane_b32 v242, s7, 15
	v_writelane_b32 v242, s8, 16
	v_writelane_b32 v242, s9, 17
	v_writelane_b32 v242, s10, 18
	v_writelane_b32 v242, s11, 19
	v_writelane_b32 v242, s12, 20
	v_writelane_b32 v242, s13, 21
	v_writelane_b32 v242, s14, 22
	v_writelane_b32 v242, s15, 23
	v_writelane_b32 v242, s16, 24
	v_writelane_b32 v242, s17, 25
	v_writelane_b32 v242, s18, 26
	v_writelane_b32 v242, s19, 27
	s_add_u32 s6, s70, 0x100000
	s_addc_u32 s7, s71, 0
	s_lshl_b32 s0, s1, 14
	v_writelane_b32 v242, s1, 28
	s_add_i32 s0, s0, 0
	v_writelane_b32 v242, s0, 29
	v_writelane_b32 v242, s65, 30
	v_writelane_b32 v242, s36, 31
	s_cmp_lt_i32 s72, 1
	s_cselect_b64 s[0:1], -1, 0
	v_writelane_b32 v242, s37, 32
	v_writelane_b32 v242, s38, 33
	v_writelane_b32 v242, s39, 34
	v_writelane_b32 v242, s40, 35
	v_writelane_b32 v242, s41, 36
	v_writelane_b32 v242, s42, 37
	v_writelane_b32 v242, s43, 38
	v_writelane_b32 v242, s44, 39
	v_writelane_b32 v242, s45, 40
	v_writelane_b32 v242, s46, 41
	s_cmp_gt_i32 s73, 0
	v_writelane_b32 v242, s47, 42
	s_cselect_b64 s[4:5], -1, 0
	v_writelane_b32 v242, s48, 43
	s_and_b64 s[4:5], s[0:1], s[4:5]
	v_writelane_b32 v242, s49, 44
	s_andn2_b64 vcc, exec, s[4:5]
	v_writelane_b32 v242, s50, 45
	v_writelane_b32 v242, s51, 46
	s_cbranch_vccnz .LBB0_22
	s_cmpk_lt_i32 s56, 0x2000
	s_cselect_b64 s[58:59], -1, 0
	s_cmpk_gt_i32 s56, 0x1fff
	s_cbranch_scc1 .LBB0_13
	s_ashr_i32 s0, s56, 31
	s_lshr_b32 s0, s0, 24
	s_add_i32 s0, s56, s0
	s_ashr_i32 s3, s0, 8
	s_and_b32 s0, s0, 0x7ffff00
	s_sub_i32 s0, s56, s0
	v_lshrrev_b32_e32 v1, 3, v142
	s_lshl_b32 s0, s0, 5
	s_ashr_i32 s1, s0, 31
	v_readlane_b32 s8, v242, 12
	v_lshl_or_b32 v28, s3, 6, v1
	s_lshl_b64 s[0:1], s[0:1], 2
	v_readlane_b32 s10, v242, 14
	v_ashrrev_i32_e32 v29, 31, v28
	v_readlane_b32 s11, v242, 15
	s_add_u32 s0, s10, s0
	v_and_b32_e32 v38, 7, v143
	v_lshlrev_b64 v[2:3], 15, v[28:29]
	v_or_b32_e32 v4, 8, v28
	v_or_b32_e32 v10, 16, v28
	v_or_b32_e32 v12, 24, v28
	v_or_b32_e32 v18, 32, v28
	v_or_b32_e32 v20, 40, v28
	v_or_b32_e32 v30, 48, v28
	v_or_b32_e32 v28, 56, v28
	s_addc_u32 s1, s11, s1
	v_lshlrev_b32_e32 v36, 4, v38
	v_mov_b32_e32 v37, 0
	v_ashrrev_i32_e32 v5, 31, v4
	v_ashrrev_i32_e32 v11, 31, v10
	v_ashrrev_i32_e32 v13, 31, v12
	v_ashrrev_i32_e32 v19, 31, v18
	v_ashrrev_i32_e32 v21, 31, v20
	v_ashrrev_i32_e32 v31, 31, v30
	v_ashrrev_i32_e32 v29, 31, v28
	v_lshl_add_u64 v[26:27], s[0:1], 0, v[36:37]
	v_lshlrev_b64 v[4:5], 15, v[4:5]
	v_lshlrev_b64 v[10:11], 15, v[10:11]
	v_lshlrev_b64 v[12:13], 15, v[12:13]
	v_lshlrev_b64 v[18:19], 15, v[18:19]
	v_lshlrev_b64 v[20:21], 15, v[20:21]
	v_lshlrev_b64 v[30:31], 15, v[30:31]
	v_lshlrev_b64 v[28:29], 15, v[28:29]
	v_lshl_add_u64 v[2:3], v[26:27], 0, v[2:3]
	v_lshl_add_u64 v[6:7], v[26:27], 0, v[4:5]
	v_lshl_add_u64 v[10:11], v[26:27], 0, v[10:11]
	v_lshl_add_u64 v[14:15], v[26:27], 0, v[12:13]
	v_lshl_add_u64 v[18:19], v[26:27], 0, v[18:19]
	v_lshl_add_u64 v[22:23], v[26:27], 0, v[20:21]
	v_lshl_add_u64 v[30:31], v[26:27], 0, v[30:31]
	v_lshl_add_u64 v[32:33], v[26:27], 0, v[28:29]
	global_load_dwordx4 v[2:5], v[2:3], off
	s_nop 0
	global_load_dwordx4 v[6:9], v[6:7], off
	s_nop 0
	global_load_dwordx4 v[10:13], v[10:11], off
	s_nop 0
	global_load_dwordx4 v[14:17], v[14:15], off
	s_nop 0
	global_load_dwordx4 v[18:21], v[18:19], off
	s_nop 0
	global_load_dwordx4 v[22:25], v[22:23], off
	s_nop 0
	global_load_dwordx4 v[26:29], v[30:31], off
	s_nop 0
	global_load_dwordx4 v[30:33], v[32:33], off
	v_readlane_b32 s0, v242, 29
	v_mul_u32_u24_e32 v38, 0x420, v38
	v_lshlrev_b32_e32 v40, 2, v1
	v_readlane_b32 s9, v242, 13
	v_add_u32_e32 v39, s0, v36
	v_add3_u32 v38, s0, v38, v40
	v_mul_u32_u24_e32 v40, 0x84, v1
	s_lshl_b32 s8, s64, 5
	v_lshl_add_u64 v[34:35], s[10:11], 0, v[36:37]
	v_lshl_add_u64 v[36:37], s[6:7], 0, v[36:37]
	s_lshl_b32 s3, s56, 5
	v_add_u32_e32 v39, v39, v40
	s_mov_b32 s9, s8
	v_mov_b32_e32 v40, v1
	s_mov_b32 s10, s56
	v_readlane_b32 s12, v242, 16
	v_readlane_b32 s13, v242, 17
	v_readlane_b32 s14, v242, 18
	v_readlane_b32 s15, v242, 19
	v_readlane_b32 s16, v242, 20
	v_readlane_b32 s17, v242, 21
	v_readlane_b32 s18, v242, 22
	v_readlane_b32 s19, v242, 23
	v_readlane_b32 s20, v242, 24
	v_readlane_b32 s21, v242, 25
	v_readlane_b32 s22, v242, 26
	v_readlane_b32 s23, v242, 27
	s_branch .LBB0_11

.LBB0_431:
	s_ashr_i32 s0, s3, 3
	s_add_i32 s0, s10, s0
	s_ashr_i32 s10, s0, 31
	s_lshr_b32 s10, s10, 26
	s_add_i32 s10, s0, s10
	s_ashr_i32 s11, s10, 6
	s_andn2_b32 s10, s10, 63
	s_sub_i32 s10, s0, s10
	s_waitcnt vmcnt(0)
	v_lshrrev_b32_e32 v3, 1, v143
	s_bfe_i32 s0, s10, 0x80000
	v_and_b32_e32 v15, 24, v3
	v_lshrrev_b32_e32 v3, 5, v143
	s_bfe_u32 s0, s0, 0x3000c
	v_and_b32_e32 v3, 4, v3
	v_bfe_u32 v4, v143, 2, 2
	s_add_i32 s12, s10, s0
	v_lshlrev_b32_e32 v2, 4, v143
	v_and_b32_e32 v1, 32, v143
	v_bfe_u32 v14, v143, 2, 4
	v_or3_b32 v3, v3, v4, v15
	v_lshrrev_b32_e32 v4, 3, v143
	s_movk_i32 s3, 0x70
	s_bfe_i32 s0, s12, 0x80000
	s_and_b32 s12, s12, 0xf8
	v_bitop3_b32 v12, v2, v1, 48 bitop3:0x6c
	v_and_b32_e32 v13, 64, v143
	v_and_or_b32 v5, v4, s3, v14
	s_movk_i32 s3, 0x60
	s_sub_i32 s10, s10, s12
	v_or_b32_e32 v1, v12, v13
	v_and_or_b32 v4, v4, s3, v3
	v_add_u32_e32 v16, 0x2000, v2
	s_lshl_b32 s11, s11, 3
	s_sext_i32_i16 s0, s0
	s_sext_i32_i8 s10, s10
	s_lshr_b32 s1, s4, 8
	v_lshl_or_b32 v132, v4, 12, v1
	v_lshrrev_b32_e32 v4, 7, v16
	s_movk_i32 s3, 0xf0
	s_lshr_b32 s0, s0, 3
	s_add_i32 s10, s11, s10
	v_lshl_or_b32 v130, v5, 12, v1
	v_and_or_b32 v5, v4, s3, v14
	s_movk_i32 s3, 0xe0
	s_lshr_b32 s5, s4, 6
	s_ashr_i32 s11, s10, 31
	s_bfe_i64 s[22:23], s[0:1], 0x100000
	v_and_or_b32 v3, v4, s3, v3
	s_lshl_b32 s3, s5, 10
	s_lshl_b64 s[12:13], s[10:11], 20
	s_lshl_b64 s[22:23], s[22:23], 20
	s_add_u32 s36, s20, s22
	s_addc_u32 s37, s21, s23
	s_add_i32 s42, s3, 0
	s_add_i32 m0, s42, 0x10000
	v_lshl_or_b32 v136, v3, 12, v1
	v_mov_b32_e32 v253, 0xa100
	global_load_dword v253, v253, s[70:71] sc1
	global_load_lds_dwordx4 v132, s[36:37]
	s_add_i32 m0, s42, 0x12000
	s_add_u32 s22, s36, 0x80000
	global_load_lds_dwordx4 v136, s[36:37]
	s_addc_u32 s23, s37, 0
	s_add_i32 m0, s42, 0x14000
	v_lshl_or_b32 v134, v5, 12, v1
	global_load_lds_dwordx4 v132, s[22:23]
	s_add_i32 m0, s42, 0x16000
	s_add_u32 s46, s44, s12
	s_addc_u32 s47, s45, s13
	s_add_i32 s43, s42, 0x2000
	global_load_lds_dwordx4 v136, s[22:23]
	s_mov_b32 m0, s42
	s_add_u32 s12, s46, 0x80000
	global_load_lds_dwordx4 v130, s[46:47]
	s_mov_b32 m0, s43
	s_addc_u32 s13, s47, 0
	s_add_i32 s60, s42, 0x4000
	global_load_lds_dwordx4 v134, s[46:47]
	s_mov_b32 m0, s60
	s_add_i32 s61, s42, 0x6000
	global_load_lds_dwordx4 v130, s[12:13]
	s_mov_b32 m0, s61
	v_mov_b32_e32 v133, 0
	global_load_lds_dwordx4 v134, s[12:13]
	v_mov_b32_e32 v137, v133
	v_mov_b32_e32 v131, v133
	v_mov_b32_e32 v135, v133
	s_cmp_eq_u32 s1, 1
	s_mov_b32 s53, 32
	s_mov_b32 s11, 0
	v_lshl_add_u64 v[10:11], s[36:37], 0, v[132:133]
	v_lshl_add_u64 v[8:9], s[36:37], 0, v[136:137]
	v_lshl_add_u64 v[6:7], s[46:47], 0, v[130:131]
	s_cselect_b64 s[12:13], -1, 0
	s_cmp_lg_u32 s1, 1
	v_lshl_add_u64 v[4:5], s[46:47], 0, v[134:135]
	s_cbranch_scc1 .LBB0_433
	s_barrier
.LBB0_433:
	v_and_b32_e32 v3, 15, v143
	v_lshlrev_b32_e32 v17, 1, v15
	v_lshlrev_b32_e32 v18, 2, v143
	s_sext_i32_i8 s54, s0
	v_lshl_or_b32 v1, s1, 6, v3
	v_lshl_or_b32 v3, v3, 6, v17
	s_lshl_b32 s0, s1, 13
	v_and_b32_e32 v18, 32, v18
	v_bitop3_b32 v19, v3, s0, v18 bitop3:0xde
	s_lshl_b32 s0, s5, 5
	s_and_b32 s5, s0, 0x60
	v_lshlrev_b32_e32 v3, 6, v143
	s_movk_i32 s0, 0x3c0
	v_and_or_b32 v3, v3, s0, v17
	s_lshl_b32 s0, s5, 7
	s_add_u32 s62, s70, 0x10000
	s_mov_b64 s[22:23], 0x80
	s_addc_u32 s63, s71, 0
	s_add_i32 m0, s42, 0x18000
	v_lshl_add_u64 v[10:11], v[10:11], 0, s[22:23]
	s_waitcnt vmcnt(2)
	s_barrier
	global_load_lds_dwordx4 v[10:11], off
	v_lshl_add_u64 v[8:9], v[8:9], 0, s[22:23]
	s_add_i32 m0, s42, 0x1a000
	s_add_i32 s66, s42, 0x8000
	s_add_i32 s67, s42, 0xa000
	v_bitop3_b32 v150, s0, v3, v18 bitop3:0xf6
	global_load_lds_dwordx4 v[8:9], off
	v_lshl_add_u64 v[6:7], v[6:7], 0, s[22:23]
	s_mov_b32 m0, s66
	s_add_u32 s0, s36, 0x80080
	global_load_lds_dwordx4 v[6:7], off
	v_lshl_add_u64 v[4:5], v[4:5], 0, s[22:23]
	s_mov_b32 m0, s67
	s_addc_u32 s1, s37, 0
	global_load_lds_dwordx4 v[4:5], off
	s_add_i32 m0, s42, 0x1c000
	v_lshl_add_u64 v[4:5], s[0:1], 0, v[132:133]
	global_load_lds_dwordx4 v[4:5], off
	v_lshl_add_u64 v[4:5], s[0:1], 0, v[136:137]
	s_add_i32 m0, s42, 0x1e000
	v_readlane_b32 s18, v242, 53
	global_load_lds_dwordx4 v[4:5], off
	v_mov_b32_e32 v3, v133
	v_readlane_b32 s19, v242, 54
	s_cmpk_lt_u32 s4, 0x100
	s_waitcnt vmcnt(6)
	s_cselect_b64 s[24:25], -1, 0
	v_lshl_add_u64 v[138:139], s[18:19], 0, v[2:3]
	v_lshlrev_b32_e32 v2, 9, v143
	v_and_b32_e32 v2, 0x70000, v2
	v_lshlrev_b32_e32 v3, 12, v14
	v_or3_b32 v2, v12, v2, v3
	v_add_u32_e32 v140, v2, v13
	v_lshlrev_b32_e32 v2, 5, v16
	s_cmpk_lt_i32 s2, 0x80
	v_and_b32_e32 v2, 0xf0000, v2
	s_cselect_b64 s[26:27], -1, 0
	s_ashr_i32 s76, s2, 3
	s_and_b32 s77, s2, 7
	v_readfirstlane_b32 s98, v253
	s_cmp_eq_u32 s98, 0
	s_cbranch_scc0 .Lxs_slow_4
	s_lshr_b32 s99, s2, 6
	s_lshl_b32 s99, s99, 3
	s_and_b32 s100, s2, 7
	s_or_b32 s76, s99, s100
	s_bfe_u32 s77, s2, 0x30003
.Lxs_slow_4:
	s_ashr_i32 s4, s2, 6
	v_or3_b32 v2, v12, v2, v3
	s_add_i32 s80, 0, 0x10000
	s_add_i32 s81, 0, 0x14000
	v_cmp_eq_u32_e64 s[0:1], 0, v143
	s_add_i32 s28, s4, 32
	s_and_b32 s30, s76, 7
	s_lshl_b32 s34, s77, 2
	v_or_b32_e32 v151, s5, v15
	v_mov_b32_e32 v141, v133
	v_add_u32_e32 v144, v2, v13
	v_mov_b32_e32 v145, v133
	s_mov_b64 s[4:5], -1
	s_mov_b32 s82, -1
	v_add_u32_e32 v152, s80, v150
	v_add_u32_e32 v153, s81, v150
	v_add_u32_e32 v154, 0, v19
	s_mov_b32 s52, 0
	s_barrier
	s_branch .LBB0_436

.LBB0_444:
	v_lshl_add_u32 v148, s10, 8, v1
	v_lshl_or_b32 v146, s54, 8, v151
	s_mov_b64 s[36:37], -1
	s_cmp_gt_i32 s82, -1
	v_cvt_pk_bf16_f32 v66, v66, v67
	v_cvt_pk_bf16_f32 v67, v68, v69
	v_cvt_pk_bf16_f32 v68, v126, v127
	v_cvt_pk_bf16_f32 v69, v128, v129
	v_cvt_pk_bf16_f32 v62, v62, v63
	v_cvt_pk_bf16_f32 v63, v64, v65
	v_cvt_pk_bf16_f32 v64, v58, v59
	v_cvt_pk_bf16_f32 v65, v60, v61
	v_cvt_pk_bf16_f32 v58, v122, v123
	v_cvt_pk_bf16_f32 v59, v124, v125
	v_cvt_pk_bf16_f32 v60, v118, v119
	v_cvt_pk_bf16_f32 v61, v120, v121
	v_cvt_pk_bf16_f32 v54, v54, v55
	v_cvt_pk_bf16_f32 v55, v56, v57
	v_cvt_pk_bf16_f32 v56, v50, v51
	v_cvt_pk_bf16_f32 v57, v52, v53
	v_cvt_pk_bf16_f32 v50, v114, v115
	v_cvt_pk_bf16_f32 v51, v116, v117
	v_cvt_pk_bf16_f32 v52, v110, v111
	v_cvt_pk_bf16_f32 v53, v112, v113
	v_cvt_pk_bf16_f32 v46, v46, v47
	v_cvt_pk_bf16_f32 v47, v48, v49
	v_cvt_pk_bf16_f32 v48, v42, v43
	v_cvt_pk_bf16_f32 v49, v44, v45
	v_cvt_pk_bf16_f32 v42, v106, v107
	v_cvt_pk_bf16_f32 v43, v108, v109
	v_cvt_pk_bf16_f32 v44, v102, v103
	v_cvt_pk_bf16_f32 v45, v104, v105
	v_cvt_pk_bf16_f32 v38, v38, v39
	v_cvt_pk_bf16_f32 v39, v40, v41
	v_cvt_pk_bf16_f32 v40, v98, v99
	v_cvt_pk_bf16_f32 v41, v100, v101
	v_cvt_pk_bf16_f32 v34, v34, v35
	v_cvt_pk_bf16_f32 v35, v36, v37
	v_cvt_pk_bf16_f32 v36, v94, v95
	v_cvt_pk_bf16_f32 v37, v96, v97
	v_cvt_pk_bf16_f32 v30, v30, v31
	v_cvt_pk_bf16_f32 v31, v32, v33
	v_cvt_pk_bf16_f32 v32, v26, v27
	v_cvt_pk_bf16_f32 v33, v28, v29
	v_cvt_pk_bf16_f32 v26, v90, v91
	v_cvt_pk_bf16_f32 v27, v92, v93
	v_cvt_pk_bf16_f32 v28, v86, v87
	v_cvt_pk_bf16_f32 v29, v88, v89
	v_cvt_pk_bf16_f32 v22, v22, v23
	v_cvt_pk_bf16_f32 v23, v24, v25
	v_cvt_pk_bf16_f32 v24, v18, v19
	v_cvt_pk_bf16_f32 v25, v20, v21
	v_cvt_pk_bf16_f32 v18, v82, v83
	v_cvt_pk_bf16_f32 v19, v84, v85
	v_cvt_pk_bf16_f32 v20, v78, v79
	v_cvt_pk_bf16_f32 v21, v80, v81
	v_cvt_pk_bf16_f32 v14, v14, v15
	v_cvt_pk_bf16_f32 v15, v16, v17
	v_cvt_pk_bf16_f32 v16, v10, v11
	v_cvt_pk_bf16_f32 v17, v12, v13
	v_cvt_pk_bf16_f32 v10, v74, v75
	v_cvt_pk_bf16_f32 v11, v76, v77
	v_cvt_pk_bf16_f32 v12, v70, v71
	v_cvt_pk_bf16_f32 v13, v72, v73
	s_cbranch_scc0 .LBB0_458
	s_lshl_b32 s36, s52, 3
	s_add_i32 s46, s36, s82
	s_ashr_i32 s47, s46, 31
	s_lshl_b64 s[46:47], s[46:47], 17
	v_lshl_add_u64 v[74:75], v[138:139], 0, s[46:47]
	s_movk_i32 s10, 0x2000
	v_add_co_u32_e32 v70, vcc, s10, v74
	s_movk_i32 s10, 0x4000
	s_nop 0
	v_addc_co_u32_e32 v71, vcc, 0, v75, vcc
	global_store_dwordx4 v[70:71], v[62:65], off
	v_add_co_u32_e32 v70, vcc, s10, v74
	s_movk_i32 s10, 0x6000
	s_nop 0
	v_addc_co_u32_e32 v71, vcc, 0, v75, vcc
	global_store_dwordx4 v[70:71], v[58:61], off
	v_add_co_u32_e32 v70, vcc, s10, v74
	s_mov_b32 s10, 0x8000
	s_nop 0
	v_addc_co_u32_e32 v71, vcc, 0, v75, vcc
	global_store_dwordx4 v[70:71], v[54:57], off
	v_add_co_u32_e32 v70, vcc, s10, v74
	s_mov_b32 s10, 0xa000
	s_nop 0
	v_addc_co_u32_e32 v71, vcc, 0, v75, vcc
	global_store_dwordx4 v[70:71], v[50:53], off
	v_add_co_u32_e32 v70, vcc, s10, v74
	s_mov_b32 s10, 0xc000
	s_nop 0
	v_addc_co_u32_e32 v71, vcc, 0, v75, vcc
	global_store_dwordx4 v[70:71], v[46:49], off
	v_add_co_u32_e32 v70, vcc, s10, v74
	s_mov_b32 s10, 0xe000
	s_nop 0
	v_addc_co_u32_e32 v71, vcc, 0, v75, vcc
	global_store_dwordx4 v[70:71], v[42:45], off
	v_add_co_u32_e32 v70, vcc, s10, v74
	s_mov_b32 s10, 0x10000
	s_nop 0
	v_addc_co_u32_e32 v71, vcc, 0, v75, vcc
	global_store_dwordx4 v[70:71], v[38:41], off
	v_add_co_u32_e32 v70, vcc, s10, v74
	s_mov_b32 s10, 0x12000
	s_nop 0
	v_addc_co_u32_e32 v71, vcc, 0, v75, vcc
	global_store_dwordx4 v[70:71], v[34:37], off
	v_add_co_u32_e32 v70, vcc, s10, v74
	s_mov_b32 s10, 0x14000
	s_nop 0
	v_addc_co_u32_e32 v71, vcc, 0, v75, vcc
	global_store_dwordx4 v[70:71], v[30:33], off
	v_add_co_u32_e32 v70, vcc, s10, v74
	s_mov_b32 s10, 0x16000
	s_nop 0
	v_addc_co_u32_e32 v71, vcc, 0, v75, vcc
	global_store_dwordx4 v[70:71], v[26:29], off
	v_add_co_u32_e32 v70, vcc, s10, v74
	s_mov_b32 s10, 0x18000
	s_nop 0
	v_addc_co_u32_e32 v71, vcc, 0, v75, vcc
	global_store_dwordx4 v[70:71], v[22:25], off
	v_add_co_u32_e32 v70, vcc, s10, v74
	s_mov_b32 s10, 0x1a000
	s_nop 0
	v_addc_co_u32_e32 v71, vcc, 0, v75, vcc
	global_store_dwordx4 v[70:71], v[18:21], off
	v_add_co_u32_e32 v70, vcc, s10, v74
	s_mov_b32 s10, 0x1c000
	s_nop 0
	v_addc_co_u32_e32 v71, vcc, 0, v75, vcc
	global_store_dwordx4 v[70:71], v[14:17], off
	v_add_co_u32_e32 v70, vcc, s10, v74
	global_store_dwordx4 v[74:75], v[66:69], off
	s_nop 0
	v_addc_co_u32_e32 v71, vcc, 0, v75, vcc
	v_add_co_u32_e32 v74, vcc, 0x1e000, v74
	global_store_dwordx4 v[70:71], v[10:13], off
	v_cvt_pk_bf16_f32 v70, v6, v7
	v_cvt_pk_bf16_f32 v71, v8, v9
	v_cvt_pk_bf16_f32 v72, v2, v3
	v_cvt_pk_bf16_f32 v73, v4, v5
	v_addc_co_u32_e32 v75, vcc, 0, v75, vcc
	global_store_dwordx4 v[74:75], v[70:73], off
	s_waitcnt vmcnt(0)
	s_waitcnt vmcnt(0)
	s_barrier
	s_and_saveexec_b64 s[46:47], s[0:1]
	s_cbranch_execz .LBB0_457
	s_lshl_b32 s52, s52, 6
	s_mov_b64 s[54:55], exec
	s_ashr_i32 s53, s52, 31
	s_lshl_b64 s[52:53], s[52:53], 2
	s_cmp_eq_u32 s98, 0
	s_cbranch_scc1 .Lxs_nowb_4
	buffer_wbl2 sc1
.Lxs_nowb_4:
	s_waitcnt vmcnt(0)
	v_mbcnt_lo_u32_b32 v70, s54, 0
	s_add_u32 s52, s62, s52
	v_mbcnt_hi_u32_b32 v70, s55, v70
	s_addc_u32 s53, s63, s53
	v_cmp_eq_u32_e32 vcc, 0, v70
	s_and_saveexec_b64 s[58:59], vcc
	s_cbranch_execz .LBB0_448
	s_bcnt1_i32_b64 s10, s[54:55]
	v_mov_b32_e32 v70, s10
	global_atomic_add v133, v70, s[52:53]

.LBB0_456:
	s_cmp_eq_u32 s98, 0
	s_cbranch_scc1 .Lxs_noinv_4
	buffer_inv sc1

.LBB0_457:
	s_or_b64 exec, exec, s[46:47]
	s_ashr_i32 s37, s36, 31
	s_lshl_b64 s[36:37], s[36:37], 17
	s_lshl_b32 s10, s82, 1
	v_lshl_add_u64 v[70:71], v[138:139], 0, s[36:37]
	s_lshl_b64 s[36:37], s[10:11], 13
	v_lshl_add_u64 v[70:71], v[70:71], 0, s[36:37]
	v_add_co_u32_e32 v72, vcc, 0x2000, v70
	s_nop 1
	v_addc_co_u32_e32 v73, vcc, 0, v71, vcc
	s_barrier
	global_load_dwordx4 v[102:105], v[70:71], off sc0
	global_load_dwordx4 v[98:101], v[72:73], off sc0
	v_add_co_u32_e32 v72, vcc, 0x20000, v70
	s_lshl_b32 s10, s82, 5
	s_nop 0
	v_addc_co_u32_e32 v73, vcc, 0, v71, vcc
	v_add_co_u32_e32 v74, vcc, 0x22000, v70
	s_and_b32 s10, s10, 0x7fffff80
	s_nop 0
	v_addc_co_u32_e32 v75, vcc, 0, v71, vcc
	global_load_dwordx4 v[106:109], v[72:73], off sc0
	global_load_dwordx4 v[94:97], v[74:75], off sc0
	v_add_co_u32_e32 v72, vcc, 0x40000, v70
	v_add_u32_e32 v147, s10, v148
	s_nop 0
	v_addc_co_u32_e32 v73, vcc, 0, v71, vcc
	v_add_co_u32_e32 v74, vcc, 0x42000, v70
	s_lshl_b32 s10, s82, 4
	s_nop 0
	v_addc_co_u32_e32 v75, vcc, 0, v71, vcc
	global_load_dwordx4 v[110:113], v[72:73], off sc0
	global_load_dwordx4 v[90:93], v[74:75], off sc0
	v_add_co_u32_e32 v72, vcc, 0x60000, v70
	v_and_or_b32 v160, s10, 48, v147
	s_nop 0
	v_addc_co_u32_e32 v73, vcc, 0, v71, vcc
	v_add_co_u32_e32 v74, vcc, 0x62000, v70
	v_ashrrev_i32_e32 v161, 31, v160
	s_nop 0
	v_addc_co_u32_e32 v75, vcc, 0, v71, vcc
	global_load_dwordx4 v[114:117], v[72:73], off sc0
	global_load_dwordx4 v[86:89], v[74:75], off sc0
	v_add_co_u32_e32 v72, vcc, 0x80000, v70
	v_ashrrev_i32_e32 v147, 31, v146
	s_nop 0
	v_addc_co_u32_e32 v73, vcc, 0, v71, vcc
	v_add_co_u32_e32 v74, vcc, 0x82000, v70
	s_mov_b64 s[36:37], 0
	s_nop 0
	v_addc_co_u32_e32 v75, vcc, 0, v71, vcc
	global_load_dwordx4 v[118:121], v[72:73], off sc0
	global_load_dwordx4 v[82:85], v[74:75], off sc0
	v_add_co_u32_e32 v72, vcc, 0xa0000, v70
	s_waitcnt vmcnt(9)
	v_lshlrev_b32_e32 v162, 16, v102
	v_addc_co_u32_e32 v73, vcc, 0, v71, vcc
	v_add_co_u32_e32 v74, vcc, 0xa2000, v70
	v_and_b32_e32 v163, 0xffff0000, v102
	s_nop 0
	v_addc_co_u32_e32 v75, vcc, 0, v71, vcc
	global_load_dwordx4 v[122:125], v[72:73], off sc0
	global_load_dwordx4 v[78:81], v[74:75], off sc0
	v_add_co_u32_e32 v72, vcc, 0xc0000, v70
	v_lshlrev_b32_e32 v102, 16, v103
	s_nop 0
	v_addc_co_u32_e32 v73, vcc, 0, v71, vcc
	v_add_co_u32_e32 v74, vcc, 0xc2000, v70
	v_and_b32_e32 v103, 0xffff0000, v103
	s_nop 0
	v_addc_co_u32_e32 v75, vcc, 0, v71, vcc
	global_load_dwordx4 v[126:129], v[72:73], off sc0
	s_nop 0
	global_load_dwordx4 v[74:77], v[74:75], off sc0
	v_add_co_u32_e32 v72, vcc, 0xe0000, v70
	v_pk_add_f32 v[162:163], v[162:163], 0 op_sel_hi:[1,0]
	s_nop 0
	v_addc_co_u32_e32 v73, vcc, 0, v71, vcc
	v_add_co_u32_e32 v70, vcc, 0xe2000, v70
	v_pk_add_f32 v[102:103], v[102:103], 0 op_sel_hi:[1,0]
	s_nop 0
	v_addc_co_u32_e32 v71, vcc, 0, v71, vcc
	global_load_dwordx4 v[156:159], v[72:73], off sc0
	s_nop 0
	global_load_dwordx4 v[70:73], v[70:71], off sc0
	v_lshlrev_b32_e32 v164, 16, v104
	v_and_b32_e32 v165, 0xffff0000, v104
	v_lshlrev_b32_e32 v104, 16, v105
	v_and_b32_e32 v105, 0xffff0000, v105
	s_waitcnt vmcnt(13)
	v_lshlrev_b32_e32 v166, 16, v106
	v_and_b32_e32 v167, 0xffff0000, v106
	v_lshlrev_b32_e32 v106, 16, v107
	v_and_b32_e32 v107, 0xffff0000, v107
	v_pk_add_f32 v[164:165], v[164:165], 0 op_sel_hi:[1,0]
	v_pk_add_f32 v[104:105], v[104:105], 0 op_sel_hi:[1,0]
	v_pk_add_f32 v[102:103], v[102:103], v[106:107]
	v_pk_add_f32 v[106:107], v[162:163], v[166:167]
	v_lshlrev_b32_e32 v162, 16, v108
	v_and_b32_e32 v163, 0xffff0000, v108
	v_lshlrev_b32_e32 v108, 16, v109
	v_and_b32_e32 v109, 0xffff0000, v109
	v_pk_add_f32 v[104:105], v[104:105], v[108:109]
	v_pk_add_f32 v[108:109], v[164:165], v[162:163]
	s_waitcnt vmcnt(11)
	v_lshlrev_b32_e32 v162, 16, v110
	v_and_b32_e32 v163, 0xffff0000, v110
	v_lshlrev_b32_e32 v110, 16, v111
	v_and_b32_e32 v111, 0xffff0000, v111
	v_pk_add_f32 v[102:103], v[102:103], v[110:111]
	v_lshlrev_b32_e32 v110, 16, v112
	v_and_b32_e32 v111, 0xffff0000, v112
	v_lshlrev_b32_e32 v112, 16, v113
	v_and_b32_e32 v113, 0xffff0000, v113
	v_pk_add_f32 v[106:107], v[106:107], v[162:163]
	v_pk_add_f32 v[108:109], v[108:109], v[110:111]
	v_pk_add_f32 v[104:105], v[104:105], v[112:113]
	s_waitcnt vmcnt(9)
	v_lshlrev_b32_e32 v110, 16, v114
	v_and_b32_e32 v111, 0xffff0000, v114
	v_lshlrev_b32_e32 v112, 16, v115
	v_and_b32_e32 v113, 0xffff0000, v115
	v_pk_add_f32 v[102:103], v[102:103], v[112:113]
	v_pk_add_f32 v[106:107], v[106:107], v[110:111]
	v_lshlrev_b32_e32 v110, 16, v116
	v_and_b32_e32 v111, 0xffff0000, v116
	v_lshlrev_b32_e32 v112, 16, v117
	v_and_b32_e32 v113, 0xffff0000, v117
	v_pk_add_f32 v[104:105], v[104:105], v[112:113]
	v_pk_add_f32 v[108:109], v[108:109], v[110:111]
	s_waitcnt vmcnt(7)
	v_lshlrev_b32_e32 v110, 16, v118
	v_and_b32_e32 v111, 0xffff0000, v118
	v_lshlrev_b32_e32 v112, 16, v119
	v_and_b32_e32 v113, 0xffff0000, v119
	v_pk_add_f32 v[106:107], v[106:107], v[110:111]
	v_pk_add_f32 v[102:103], v[102:103], v[112:113]
	v_lshlrev_b32_e32 v110, 16, v120
	v_and_b32_e32 v111, 0xffff0000, v120
	v_lshlrev_b32_e32 v112, 16, v121
	v_and_b32_e32 v113, 0xffff0000, v121
	v_pk_add_f32 v[108:109], v[108:109], v[110:111]
	v_pk_add_f32 v[104:105], v[104:105], v[112:113]
	s_waitcnt vmcnt(5)
	v_lshlrev_b32_e32 v110, 16, v122
	v_and_b32_e32 v111, 0xffff0000, v122
	v_lshlrev_b32_e32 v112, 16, v123
	v_and_b32_e32 v113, 0xffff0000, v123
	v_pk_add_f32 v[102:103], v[102:103], v[112:113]
	v_pk_add_f32 v[106:107], v[106:107], v[110:111]
	v_lshlrev_b32_e32 v110, 16, v124
	v_and_b32_e32 v111, 0xffff0000, v124
	v_lshlrev_b32_e32 v112, 16, v125
	v_and_b32_e32 v113, 0xffff0000, v125
	v_pk_add_f32 v[104:105], v[104:105], v[112:113]
	v_pk_add_f32 v[108:109], v[108:109], v[110:111]
	s_waitcnt vmcnt(3)
	v_lshlrev_b32_e32 v110, 16, v126
	v_and_b32_e32 v111, 0xffff0000, v126
	v_lshlrev_b32_e32 v112, 16, v127
	v_and_b32_e32 v113, 0xffff0000, v127
	v_pk_add_f32 v[106:107], v[106:107], v[110:111]
	v_pk_add_f32 v[102:103], v[102:103], v[112:113]
	v_lshlrev_b32_e32 v110, 16, v128
	v_and_b32_e32 v111, 0xffff0000, v128
	v_lshlrev_b32_e32 v112, 16, v129
	v_and_b32_e32 v113, 0xffff0000, v129
	v_pk_add_f32 v[108:109], v[108:109], v[110:111]
	v_pk_add_f32 v[104:105], v[104:105], v[112:113]
	s_waitcnt vmcnt(1)
	v_lshlrev_b32_e32 v110, 16, v156
	v_and_b32_e32 v111, 0xffff0000, v156
	v_lshlrev_b32_e32 v112, 16, v157
	v_and_b32_e32 v113, 0xffff0000, v157
	v_pk_add_f32 v[102:103], v[102:103], v[112:113]
	v_pk_add_f32 v[106:107], v[106:107], v[110:111]
	v_lshlrev_b32_e32 v110, 16, v158
	v_and_b32_e32 v111, 0xffff0000, v158
	v_lshlrev_b32_e32 v112, 16, v159
	v_and_b32_e32 v113, 0xffff0000, v159
	v_pk_add_f32 v[112:113], v[104:105], v[112:113]
	v_pk_add_f32 v[108:109], v[108:109], v[110:111]
	v_cvt_pk_bf16_f32 v105, v102, v103
	v_lshlrev_b64 v[102:103], 12, v[160:161]
	v_cvt_pk_bf16_f32 v104, v106, v107
	v_cvt_pk_bf16_f32 v106, v108, v109
	v_lshl_add_u64 v[108:109], s[40:41], 0, v[102:103]
	v_cvt_pk_bf16_f32 v107, v112, v113
	v_lshl_add_u64 v[108:109], v[146:147], 1, v[108:109]
	global_store_dwordx4 v[108:109], v[104:107], off
	v_lshlrev_b32_e32 v108, 16, v94
	v_and_b32_e32 v109, 0xffff0000, v94
	v_lshlrev_b32_e32 v104, 16, v98
	v_and_b32_e32 v105, 0xffff0000, v98
	v_lshlrev_b32_e32 v98, 16, v99
	v_and_b32_e32 v99, 0xffff0000, v99
	v_pk_add_f32 v[104:105], v[104:105], 0 op_sel_hi:[1,0]
	v_pk_add_f32 v[98:99], v[98:99], 0 op_sel_hi:[1,0]
	v_lshlrev_b32_e32 v106, 16, v100
	v_and_b32_e32 v107, 0xffff0000, v100
	v_lshlrev_b32_e32 v100, 16, v101
	v_and_b32_e32 v101, 0xffff0000, v101
	v_lshlrev_b32_e32 v94, 16, v95
	v_and_b32_e32 v95, 0xffff0000, v95
	v_pk_add_f32 v[106:107], v[106:107], 0 op_sel_hi:[1,0]
	v_pk_add_f32 v[100:101], v[100:101], 0 op_sel_hi:[1,0]
	v_pk_add_f32 v[94:95], v[98:99], v[94:95]
	v_pk_add_f32 v[98:99], v[104:105], v[108:109]
	v_lshlrev_b32_e32 v104, 16, v96
	v_and_b32_e32 v105, 0xffff0000, v96
	v_lshlrev_b32_e32 v96, 16, v97
	v_and_b32_e32 v97, 0xffff0000, v97
	v_pk_add_f32 v[96:97], v[100:101], v[96:97]
	v_pk_add_f32 v[100:101], v[106:107], v[104:105]
	v_lshlrev_b32_e32 v104, 16, v90
	v_and_b32_e32 v105, 0xffff0000, v90
	v_lshlrev_b32_e32 v90, 16, v91
	v_and_b32_e32 v91, 0xffff0000, v91
	v_pk_add_f32 v[90:91], v[94:95], v[90:91]
	v_lshlrev_b32_e32 v94, 16, v92
	v_and_b32_e32 v95, 0xffff0000, v92
	v_lshlrev_b32_e32 v92, 16, v93
	v_and_b32_e32 v93, 0xffff0000, v93
	v_pk_add_f32 v[98:99], v[98:99], v[104:105]
	v_pk_add_f32 v[92:93], v[96:97], v[92:93]
	v_lshlrev_b32_e32 v96, 16, v86
	v_and_b32_e32 v97, 0xffff0000, v86
	v_lshlrev_b32_e32 v86, 16, v87
	v_and_b32_e32 v87, 0xffff0000, v87
	v_pk_add_f32 v[94:95], v[100:101], v[94:95]
	v_pk_add_f32 v[86:87], v[90:91], v[86:87]
	v_pk_add_f32 v[90:91], v[98:99], v[96:97]
	v_lshlrev_b32_e32 v96, 16, v88
	v_and_b32_e32 v97, 0xffff0000, v88
	v_lshlrev_b32_e32 v88, 16, v89
	v_and_b32_e32 v89, 0xffff0000, v89
	v_pk_add_f32 v[88:89], v[92:93], v[88:89]
	v_pk_add_f32 v[92:93], v[94:95], v[96:97]
	v_lshlrev_b32_e32 v94, 16, v82
	v_and_b32_e32 v95, 0xffff0000, v82
	v_lshlrev_b32_e32 v82, 16, v83
	v_and_b32_e32 v83, 0xffff0000, v83
	v_pk_add_f32 v[82:83], v[86:87], v[82:83]
	v_lshlrev_b32_e32 v86, 16, v84
	v_and_b32_e32 v87, 0xffff0000, v84
	v_lshlrev_b32_e32 v84, 16, v85
	v_and_b32_e32 v85, 0xffff0000, v85
	v_pk_add_f32 v[90:91], v[90:91], v[94:95]
	v_pk_add_f32 v[84:85], v[88:89], v[84:85]
	v_lshlrev_b32_e32 v88, 16, v78
	v_and_b32_e32 v89, 0xffff0000, v78
	v_lshlrev_b32_e32 v78, 16, v79
	v_and_b32_e32 v79, 0xffff0000, v79
	v_pk_add_f32 v[86:87], v[92:93], v[86:87]
	v_pk_add_f32 v[78:79], v[82:83], v[78:79]
	v_pk_add_f32 v[82:83], v[90:91], v[88:89]
	v_lshlrev_b32_e32 v88, 16, v80
	v_and_b32_e32 v89, 0xffff0000, v80
	v_lshlrev_b32_e32 v80, 16, v81
	v_and_b32_e32 v81, 0xffff0000, v81
	v_pk_add_f32 v[80:81], v[84:85], v[80:81]
	v_pk_add_f32 v[84:85], v[86:87], v[88:89]
	v_lshlrev_b32_e32 v86, 16, v74
	v_and_b32_e32 v87, 0xffff0000, v74
	v_lshlrev_b32_e32 v74, 16, v75
	v_and_b32_e32 v75, 0xffff0000, v75
	v_pk_add_f32 v[74:75], v[78:79], v[74:75]
	v_lshlrev_b32_e32 v78, 16, v76
	v_and_b32_e32 v79, 0xffff0000, v76
	v_lshlrev_b32_e32 v76, 16, v77
	v_and_b32_e32 v77, 0xffff0000, v77
	v_pk_add_f32 v[78:79], v[84:85], v[78:79]
	s_waitcnt vmcnt(1)
	v_lshlrev_b32_e32 v84, 16, v70
	v_and_b32_e32 v85, 0xffff0000, v70
	v_lshlrev_b32_e32 v70, 16, v71
	v_and_b32_e32 v71, 0xffff0000, v71
	v_pk_add_f32 v[82:83], v[82:83], v[86:87]
	v_pk_add_f32 v[80:81], v[80:81], v[76:77]
	v_pk_add_f32 v[76:77], v[74:75], v[70:71]
	v_lshlrev_b32_e32 v70, 16, v72
	v_and_b32_e32 v71, 0xffff0000, v72
	v_lshlrev_b32_e32 v72, 16, v73
	v_and_b32_e32 v73, 0xffff0000, v73
	v_pk_add_f32 v[74:75], v[82:83], v[84:85]
	v_pk_add_f32 v[72:73], v[80:81], v[72:73]
	v_pk_add_f32 v[70:71], v[78:79], v[70:71]

.LBB0_692:
	s_ashr_i32 s8, s3, 3
	s_waitcnt vmcnt(0)
	v_lshrrev_b32_e32 v4, 1, v143
	s_add_i32 s5, s5, s8
	v_and_b32_e32 v14, 24, v4
	v_lshrrev_b32_e32 v4, 5, v143
	s_ashr_i32 s8, s5, 31
	v_and_b32_e32 v4, 4, v4
	v_bfe_u32 v5, v143, 2, 2
	s_lshr_b32 s8, s8, 26
	v_lshlrev_b32_e32 v2, 4, v143
	v_and_b32_e32 v1, 32, v143
	v_bfe_u32 v3, v143, 2, 4
	v_or3_b32 v4, v4, v5, v14
	v_lshrrev_b32_e32 v5, 3, v143
	s_movk_i32 s1, 0x70
	s_add_i32 s8, s5, s8
	v_bitop3_b32 v12, v2, v1, 48 bitop3:0x6c
	v_and_b32_e32 v13, 64, v143
	v_and_or_b32 v6, v5, s1, v3
	s_movk_i32 s1, 0x60
	s_ashr_i32 s9, s8, 6
	s_andn2_b32 s8, s8, 63
	v_or_b32_e32 v1, v12, v13
	v_and_or_b32 v5, v5, s1, v4
	s_sub_i32 s8, s5, s8
	v_lshrrev_b32_e32 v1, 1, v1
	v_mul_u32_u24_e32 v5, 0x1600, v5
	s_bfe_i32 s5, s8, 0x80000
	v_or_b32_e32 v5, v5, v1
	s_bfe_u32 s5, s5, 0x3000c
	v_lshlrev_b32_e32 v132, 1, v5
	v_add_u32_e32 v5, 0x2000, v2
	s_add_i32 s10, s8, s5
	v_lshrrev_b32_e32 v5, 7, v5
	s_movk_i32 s1, 0xf0
	s_bfe_i32 s5, s10, 0x80000
	s_and_b32 s10, s10, 0xf8
	v_and_or_b32 v3, v5, s1, v3
	s_movk_i32 s1, 0xe0
	s_sext_i32_i16 s11, s5
	s_sub_i32 s8, s8, s10
	v_and_or_b32 v4, v5, s1, v4
	s_lshr_b32 s1, s4, 6
	s_lshl_b32 s9, s9, 3
	s_sext_i32_i8 s8, s8
	s_ashr_i32 s10, s11, 3
	s_lshr_b32 s0, s4, 8
	s_lshl_b32 s3, s1, 10
	s_lshr_b32 s5, s11, 3
	s_add_i32 s8, s9, s8
	s_mul_hi_i32 s11, s10, 0x2c0000
	s_mul_i32 s10, s10, 0x2c0000
	v_mul_u32_u24_e32 v16, 0x1600, v3
	s_add_u32 s34, s92, s10
	v_or_b32_e32 v3, v16, v1
	s_addc_u32 s35, s93, s11
	s_add_i32 s42, s3, 0
	v_mul_u32_u24_e32 v15, 0x1600, v6
	v_lshlrev_b32_e32 v134, 1, v3
	v_mul_u32_u24_e32 v3, 0x1600, v4
	s_add_i32 m0, s42, 0x10000
	v_or_b32_e32 v6, v1, v15
	v_or_b32_e32 v1, v3, v1
	v_mov_b32_e32 v253, 0xa100
	global_load_dword v253, v253, s[70:71] sc1
	global_load_lds_dwordx4 v132, s[34:35]
	s_add_i32 m0, s42, 0x12000
	v_lshlrev_b32_e32 v136, 1, v1
	s_add_u32 s10, s34, 0x160000
	global_load_lds_dwordx4 v136, s[34:35]
	s_addc_u32 s11, s35, 0
	s_add_i32 m0, s42, 0x14000
	s_mul_i32 s12, s8, 0x2c0000
	global_load_lds_dwordx4 v132, s[10:11]
	s_add_i32 m0, s42, 0x16000
	s_mul_hi_i32 s9, s8, 0x2c0000
	s_add_u32 s30, s38, s12
	s_addc_u32 s31, s39, s9
	s_add_i32 s43, s42, 0x2000
	v_lshlrev_b32_e32 v130, 1, v6
	global_load_lds_dwordx4 v136, s[10:11]
	s_mov_b32 m0, s42
	s_add_u32 s10, s30, 0x160000
	global_load_lds_dwordx4 v130, s[30:31]
	s_mov_b32 m0, s43
	s_addc_u32 s11, s31, 0
	s_add_i32 s54, s42, 0x4000
	global_load_lds_dwordx4 v134, s[30:31]
	s_mov_b32 m0, s54
	s_add_i32 s55, s42, 0x6000
	global_load_lds_dwordx4 v130, s[10:11]
	s_mov_b32 m0, s55
	v_mov_b32_e32 v133, 0
	global_load_lds_dwordx4 v134, s[10:11]
	v_mov_b32_e32 v137, v133
	v_mov_b32_e32 v131, v133
	v_mov_b32_e32 v135, v133
	s_cmp_eq_u32 s0, 1
	s_mov_b32 s14, s56
	s_mov_b32 s9, 0
	v_lshl_add_u64 v[10:11], s[34:35], 0, v[132:133]
	v_lshl_add_u64 v[8:9], s[34:35], 0, v[136:137]
	v_lshl_add_u64 v[6:7], s[30:31], 0, v[130:131]
	s_cselect_b64 s[10:11], -1, 0
	s_cmp_lg_u32 s0, 1
	v_lshl_add_u64 v[4:5], s[30:31], 0, v[134:135]
	s_cbranch_scc1 .LBB0_694
	s_barrier
.LBB0_694:
	s_add_u32 s56, s70, 0x11000
	v_and_b32_e32 v3, 15, v143
	v_lshlrev_b32_e32 v17, 1, v14
	v_lshlrev_b32_e32 v18, 2, v143
	s_addc_u32 s57, s71, 0
	v_lshl_or_b32 v1, s0, 6, v3
	v_lshl_or_b32 v3, v3, 6, v17
	s_lshl_b32 s0, s0, 13
	v_and_b32_e32 v18, 32, v18
	v_bitop3_b32 v19, v3, s0, v18 bitop3:0xde
	s_lshl_b32 s0, s1, 5
	s_mov_b64 s[12:13], 0x80
	s_sext_i32_i8 s46, s5
	s_and_b32 s5, s0, 0x60
	v_lshlrev_b32_e32 v3, 6, v143
	s_movk_i32 s0, 0x3c0
	s_add_i32 m0, s42, 0x18000
	v_lshl_add_u64 v[10:11], v[10:11], 0, s[12:13]
	v_and_or_b32 v3, v3, s0, v17
	s_lshl_b32 s0, s5, 7
	s_waitcnt vmcnt(2)
	s_barrier
	global_load_lds_dwordx4 v[10:11], off
	v_lshl_add_u64 v[8:9], v[8:9], 0, s[12:13]
	s_add_i32 m0, s42, 0x1a000
	s_add_i32 s58, s42, 0x8000
	s_add_i32 s59, s42, 0xa000
	v_bitop3_b32 v150, s0, v3, v18 bitop3:0xf6
	global_load_lds_dwordx4 v[8:9], off
	v_lshl_add_u64 v[6:7], v[6:7], 0, s[12:13]
	s_mov_b32 m0, s58
	s_add_u32 s0, s34, 0x160080
	global_load_lds_dwordx4 v[6:7], off
	v_lshl_add_u64 v[4:5], v[4:5], 0, s[12:13]
	s_mov_b32 m0, s59
	s_addc_u32 s1, s35, 0
	global_load_lds_dwordx4 v[4:5], off
	s_add_i32 m0, s42, 0x1c000
	v_lshl_add_u64 v[4:5], s[0:1], 0, v[132:133]
	global_load_lds_dwordx4 v[4:5], off
	v_lshl_add_u64 v[4:5], s[0:1], 0, v[136:137]
	s_add_i32 m0, s42, 0x1e000
	s_cmpk_lt_u32 s4, 0x100
	global_load_lds_dwordx4 v[4:5], off
	s_cselect_b64 s[20:21], -1, 0
	s_cmpk_lt_i32 s2, 0x80
	s_cselect_b64 s[22:23], -1, 0
	s_and_b32 s61, s2, 7
	s_ashr_i32 s4, s2, 6
	v_readlane_b32 s18, v242, 53
	s_ashr_i32 s60, s2, 3
	v_readfirstlane_b32 s98, v253
	s_cmp_eq_u32 s98, 0
	s_cbranch_scc0 .Lxs_slow_7
	s_lshr_b32 s99, s2, 6
	s_lshl_b32 s99, s99, 3
	s_and_b32 s100, s2, 7
	s_or_b32 s60, s99, s100
	s_bfe_u32 s61, s2, 0x30003
.Lxs_slow_7:
	s_add_i32 s62, s4, 32
	s_mul_i32 s4, s61, 10
	v_mov_b32_e32 v3, v133
	v_readlane_b32 s19, v242, 54
	s_and_b32 s63, s60, 7
	s_add_i32 s4, s4, 8
	s_waitcnt vmcnt(6)
	v_lshl_add_u64 v[138:139], s[18:19], 0, v[2:3]
	s_cmp_lt_u32 s61, 4
	s_mul_i32 s24, s61, 12
	v_add_u16_e32 v2, v12, v13
	s_cselect_b32 s66, 12, 10
	s_cselect_b32 s24, s24, s4
	v_lshrrev_b16_e32 v2, 1, v2
	s_add_i32 s67, 0, 0x10000
	s_add_i32 s76, 0, 0x14000
	v_cmp_eq_u32_e64 s[0:1], 0, v143
	v_or_b32_e32 v151, s5, v14
	v_add_lshl_u32 v140, v15, v2, 1
	v_mov_b32_e32 v141, v133
	v_add_lshl_u32 v144, v16, v2, 1
	v_mov_b32_e32 v145, v133
	s_mov_b64 s[4:5], -1
	s_movk_i32 s47, 0x58
	s_mov_b32 s77, -1
	v_add_u32_e32 v152, s67, v150
	v_add_u32_e32 v153, s76, v150
	v_add_u32_e32 v154, 0, v19
	s_mov_b32 s52, 0
	s_barrier
	s_branch .LBB0_697

.LBB0_705:
	v_lshl_add_u32 v148, s8, 8, v1
	v_lshl_or_b32 v146, s46, 8, v151
	s_mov_b64 s[30:31], -1
	s_cmp_gt_i32 s77, -1
	v_cvt_pk_bf16_f32 v66, v66, v67
	v_cvt_pk_bf16_f32 v67, v68, v69
	v_cvt_pk_bf16_f32 v68, v126, v127
	v_cvt_pk_bf16_f32 v69, v128, v129
	v_cvt_pk_bf16_f32 v62, v62, v63
	v_cvt_pk_bf16_f32 v63, v64, v65
	v_cvt_pk_bf16_f32 v64, v58, v59
	v_cvt_pk_bf16_f32 v65, v60, v61
	v_cvt_pk_bf16_f32 v58, v122, v123
	v_cvt_pk_bf16_f32 v59, v124, v125
	v_cvt_pk_bf16_f32 v60, v118, v119
	v_cvt_pk_bf16_f32 v61, v120, v121
	v_cvt_pk_bf16_f32 v54, v54, v55
	v_cvt_pk_bf16_f32 v55, v56, v57
	v_cvt_pk_bf16_f32 v56, v50, v51
	v_cvt_pk_bf16_f32 v57, v52, v53
	v_cvt_pk_bf16_f32 v50, v114, v115
	v_cvt_pk_bf16_f32 v51, v116, v117
	v_cvt_pk_bf16_f32 v52, v110, v111
	v_cvt_pk_bf16_f32 v53, v112, v113
	v_cvt_pk_bf16_f32 v46, v46, v47
	v_cvt_pk_bf16_f32 v47, v48, v49
	v_cvt_pk_bf16_f32 v48, v42, v43
	v_cvt_pk_bf16_f32 v49, v44, v45
	v_cvt_pk_bf16_f32 v42, v106, v107
	v_cvt_pk_bf16_f32 v43, v108, v109
	v_cvt_pk_bf16_f32 v44, v102, v103
	v_cvt_pk_bf16_f32 v45, v104, v105
	v_cvt_pk_bf16_f32 v38, v38, v39
	v_cvt_pk_bf16_f32 v39, v40, v41
	v_cvt_pk_bf16_f32 v40, v98, v99
	v_cvt_pk_bf16_f32 v41, v100, v101
	v_cvt_pk_bf16_f32 v34, v34, v35
	v_cvt_pk_bf16_f32 v35, v36, v37
	v_cvt_pk_bf16_f32 v36, v94, v95
	v_cvt_pk_bf16_f32 v37, v96, v97
	v_cvt_pk_bf16_f32 v30, v30, v31
	v_cvt_pk_bf16_f32 v31, v32, v33
	v_cvt_pk_bf16_f32 v32, v26, v27
	v_cvt_pk_bf16_f32 v33, v28, v29
	v_cvt_pk_bf16_f32 v26, v90, v91
	v_cvt_pk_bf16_f32 v27, v92, v93
	v_cvt_pk_bf16_f32 v28, v86, v87
	v_cvt_pk_bf16_f32 v29, v88, v89
	v_cvt_pk_bf16_f32 v22, v22, v23
	v_cvt_pk_bf16_f32 v23, v24, v25
	v_cvt_pk_bf16_f32 v24, v18, v19
	v_cvt_pk_bf16_f32 v25, v20, v21
	v_cvt_pk_bf16_f32 v18, v82, v83
	v_cvt_pk_bf16_f32 v19, v84, v85
	v_cvt_pk_bf16_f32 v20, v78, v79
	v_cvt_pk_bf16_f32 v21, v80, v81
	v_cvt_pk_bf16_f32 v14, v14, v15
	v_cvt_pk_bf16_f32 v15, v16, v17
	v_cvt_pk_bf16_f32 v16, v10, v11
	v_cvt_pk_bf16_f32 v17, v12, v13
	v_cvt_pk_bf16_f32 v10, v74, v75
	v_cvt_pk_bf16_f32 v11, v76, v77
	v_cvt_pk_bf16_f32 v12, v70, v71
	v_cvt_pk_bf16_f32 v13, v72, v73
	s_cbranch_scc0 .LBB0_719
	s_lshl_b32 s30, s52, 3
	s_add_i32 s34, s30, s77
	s_ashr_i32 s35, s34, 31
	s_lshl_b64 s[34:35], s[34:35], 17
	v_lshl_add_u64 v[74:75], v[138:139], 0, s[34:35]
	s_movk_i32 s8, 0x2000
	v_add_co_u32_e32 v70, vcc, s8, v74
	s_movk_i32 s8, 0x4000
	s_nop 0
	v_addc_co_u32_e32 v71, vcc, 0, v75, vcc
	global_store_dwordx4 v[70:71], v[62:65], off
	v_add_co_u32_e32 v70, vcc, s8, v74
	s_movk_i32 s8, 0x6000
	s_nop 0
	v_addc_co_u32_e32 v71, vcc, 0, v75, vcc
	global_store_dwordx4 v[70:71], v[58:61], off
	v_add_co_u32_e32 v70, vcc, s8, v74
	s_mov_b32 s8, 0x8000
	s_nop 0
	v_addc_co_u32_e32 v71, vcc, 0, v75, vcc
	global_store_dwordx4 v[70:71], v[54:57], off
	v_add_co_u32_e32 v70, vcc, s8, v74
	s_mov_b32 s8, 0xa000
	s_nop 0
	v_addc_co_u32_e32 v71, vcc, 0, v75, vcc
	global_store_dwordx4 v[70:71], v[50:53], off
	v_add_co_u32_e32 v70, vcc, s8, v74
	s_mov_b32 s8, 0xc000
	s_nop 0
	v_addc_co_u32_e32 v71, vcc, 0, v75, vcc
	global_store_dwordx4 v[70:71], v[46:49], off
	v_add_co_u32_e32 v70, vcc, s8, v74
	s_mov_b32 s8, 0xe000
	s_nop 0
	v_addc_co_u32_e32 v71, vcc, 0, v75, vcc
	global_store_dwordx4 v[70:71], v[42:45], off
	v_add_co_u32_e32 v70, vcc, s8, v74
	s_mov_b32 s8, 0x10000
	s_nop 0
	v_addc_co_u32_e32 v71, vcc, 0, v75, vcc
	global_store_dwordx4 v[70:71], v[38:41], off
	v_add_co_u32_e32 v70, vcc, s8, v74
	s_mov_b32 s8, 0x12000
	s_nop 0
	v_addc_co_u32_e32 v71, vcc, 0, v75, vcc
	global_store_dwordx4 v[70:71], v[34:37], off
	v_add_co_u32_e32 v70, vcc, s8, v74
	s_mov_b32 s8, 0x14000
	s_nop 0
	v_addc_co_u32_e32 v71, vcc, 0, v75, vcc
	global_store_dwordx4 v[70:71], v[30:33], off
	v_add_co_u32_e32 v70, vcc, s8, v74
	s_mov_b32 s8, 0x16000
	s_nop 0
	v_addc_co_u32_e32 v71, vcc, 0, v75, vcc
	global_store_dwordx4 v[70:71], v[26:29], off
	v_add_co_u32_e32 v70, vcc, s8, v74
	s_mov_b32 s8, 0x18000
	s_nop 0
	v_addc_co_u32_e32 v71, vcc, 0, v75, vcc
	global_store_dwordx4 v[70:71], v[22:25], off
	v_add_co_u32_e32 v70, vcc, s8, v74
	s_mov_b32 s8, 0x1a000
	s_nop 0
	v_addc_co_u32_e32 v71, vcc, 0, v75, vcc
	global_store_dwordx4 v[70:71], v[18:21], off
	v_add_co_u32_e32 v70, vcc, s8, v74
	s_mov_b32 s8, 0x1c000
	s_nop 0
	v_addc_co_u32_e32 v71, vcc, 0, v75, vcc
	global_store_dwordx4 v[70:71], v[14:17], off
	v_add_co_u32_e32 v70, vcc, s8, v74
	global_store_dwordx4 v[74:75], v[66:69], off
	s_nop 0
	v_addc_co_u32_e32 v71, vcc, 0, v75, vcc
	v_add_co_u32_e32 v74, vcc, 0x1e000, v74
	global_store_dwordx4 v[70:71], v[10:13], off
	v_cvt_pk_bf16_f32 v70, v6, v7
	v_cvt_pk_bf16_f32 v71, v8, v9
	v_cvt_pk_bf16_f32 v72, v2, v3
	v_cvt_pk_bf16_f32 v73, v4, v5
	v_addc_co_u32_e32 v75, vcc, 0, v75, vcc
	global_store_dwordx4 v[74:75], v[70:73], off
	s_waitcnt vmcnt(0)
	s_waitcnt vmcnt(0)
	s_barrier
	s_and_saveexec_b64 s[34:35], s[0:1]
	s_cbranch_execz .LBB0_718
	s_lshl_b32 s36, s52, 6
	s_mov_b64 s[46:47], exec
	s_ashr_i32 s37, s36, 31
	s_lshl_b64 s[36:37], s[36:37], 2
	s_cmp_eq_u32 s98, 0
	s_cbranch_scc1 .Lxs_nowb_7
	buffer_wbl2 sc1
.Lxs_nowb_7:
	s_waitcnt vmcnt(0)
	v_mbcnt_lo_u32_b32 v70, s46, 0
	s_add_u32 s36, s56, s36
	v_mbcnt_hi_u32_b32 v70, s47, v70
	s_addc_u32 s37, s57, s37
	v_cmp_eq_u32_e32 vcc, 0, v70
	s_and_saveexec_b64 s[52:53], vcc
	s_cbranch_execz .LBB0_709
	s_bcnt1_i32_b64 s8, s[46:47]
	v_mov_b32_e32 v70, s8
	global_atomic_add v133, v70, s[36:37]

.LBB0_718:
	s_or_b64 exec, exec, s[34:35]
	s_ashr_i32 s31, s30, 31
	s_lshl_b64 s[30:31], s[30:31], 17
	s_lshl_b32 s8, s77, 1
	v_lshl_add_u64 v[70:71], v[138:139], 0, s[30:31]
	s_lshl_b64 s[30:31], s[8:9], 13
	v_lshl_add_u64 v[70:71], v[70:71], 0, s[30:31]
	v_add_co_u32_e32 v72, vcc, 0x2000, v70
	s_nop 1
	v_addc_co_u32_e32 v73, vcc, 0, v71, vcc
	s_barrier
	global_load_dwordx4 v[102:105], v[70:71], off sc0
	global_load_dwordx4 v[98:101], v[72:73], off sc0
	v_add_co_u32_e32 v72, vcc, 0x20000, v70
	s_lshl_b32 s8, s77, 5
	s_nop 0
	v_addc_co_u32_e32 v73, vcc, 0, v71, vcc
	v_add_co_u32_e32 v74, vcc, 0x22000, v70
	s_and_b32 s8, s8, 0x7fffff80
	s_nop 0
	v_addc_co_u32_e32 v75, vcc, 0, v71, vcc
	global_load_dwordx4 v[106:109], v[72:73], off sc0
	global_load_dwordx4 v[94:97], v[74:75], off sc0
	v_add_co_u32_e32 v72, vcc, 0x40000, v70
	v_add_u32_e32 v147, s8, v148
	s_nop 0
	v_addc_co_u32_e32 v73, vcc, 0, v71, vcc
	v_add_co_u32_e32 v74, vcc, 0x42000, v70
	s_lshl_b32 s8, s77, 4
	s_nop 0
	v_addc_co_u32_e32 v75, vcc, 0, v71, vcc
	global_load_dwordx4 v[110:113], v[72:73], off sc0
	global_load_dwordx4 v[90:93], v[74:75], off sc0
	v_add_co_u32_e32 v72, vcc, 0x60000, v70
	v_and_or_b32 v160, s8, 48, v147
	s_nop 0
	v_addc_co_u32_e32 v73, vcc, 0, v71, vcc
	v_add_co_u32_e32 v74, vcc, 0x62000, v70
	v_ashrrev_i32_e32 v161, 31, v160
	s_nop 0
	v_addc_co_u32_e32 v75, vcc, 0, v71, vcc
	global_load_dwordx4 v[114:117], v[72:73], off sc0
	global_load_dwordx4 v[86:89], v[74:75], off sc0
	v_add_co_u32_e32 v72, vcc, 0x80000, v70
	v_ashrrev_i32_e32 v147, 31, v146
	s_nop 0
	v_addc_co_u32_e32 v73, vcc, 0, v71, vcc
	v_add_co_u32_e32 v74, vcc, 0x82000, v70
	s_mov_b64 s[30:31], 0
	s_nop 0
	v_addc_co_u32_e32 v75, vcc, 0, v71, vcc
	global_load_dwordx4 v[118:121], v[72:73], off sc0
	global_load_dwordx4 v[82:85], v[74:75], off sc0
	v_add_co_u32_e32 v72, vcc, 0xa0000, v70
	s_waitcnt vmcnt(9)
	v_lshlrev_b32_e32 v162, 16, v102
	v_addc_co_u32_e32 v73, vcc, 0, v71, vcc
	v_add_co_u32_e32 v74, vcc, 0xa2000, v70
	v_and_b32_e32 v163, 0xffff0000, v102
	s_nop 0
	v_addc_co_u32_e32 v75, vcc, 0, v71, vcc
	global_load_dwordx4 v[122:125], v[72:73], off sc0
	global_load_dwordx4 v[78:81], v[74:75], off sc0
	v_add_co_u32_e32 v72, vcc, 0xc0000, v70
	v_lshlrev_b32_e32 v102, 16, v103
	s_nop 0
	v_addc_co_u32_e32 v73, vcc, 0, v71, vcc
	v_add_co_u32_e32 v74, vcc, 0xc2000, v70
	v_and_b32_e32 v103, 0xffff0000, v103
	s_nop 0
	v_addc_co_u32_e32 v75, vcc, 0, v71, vcc
	global_load_dwordx4 v[126:129], v[72:73], off sc0
	s_nop 0
	global_load_dwordx4 v[74:77], v[74:75], off sc0
	v_add_co_u32_e32 v72, vcc, 0xe0000, v70
	v_pk_add_f32 v[162:163], v[162:163], 0 op_sel_hi:[1,0]
	s_nop 0
	v_addc_co_u32_e32 v73, vcc, 0, v71, vcc
	v_add_co_u32_e32 v70, vcc, 0xe2000, v70
	v_pk_add_f32 v[102:103], v[102:103], 0 op_sel_hi:[1,0]
	s_nop 0
	v_addc_co_u32_e32 v71, vcc, 0, v71, vcc
	global_load_dwordx4 v[156:159], v[72:73], off sc0
	s_nop 0
	global_load_dwordx4 v[70:73], v[70:71], off sc0
	v_lshlrev_b32_e32 v164, 16, v104
	v_and_b32_e32 v165, 0xffff0000, v104
	v_lshlrev_b32_e32 v104, 16, v105
	v_and_b32_e32 v105, 0xffff0000, v105
	s_waitcnt vmcnt(13)
	v_lshlrev_b32_e32 v166, 16, v106
	v_and_b32_e32 v167, 0xffff0000, v106
	v_lshlrev_b32_e32 v106, 16, v107
	v_and_b32_e32 v107, 0xffff0000, v107
	v_pk_add_f32 v[164:165], v[164:165], 0 op_sel_hi:[1,0]
	v_pk_add_f32 v[104:105], v[104:105], 0 op_sel_hi:[1,0]
	v_pk_add_f32 v[102:103], v[102:103], v[106:107]
	v_pk_add_f32 v[106:107], v[162:163], v[166:167]
	v_lshlrev_b32_e32 v162, 16, v108
	v_and_b32_e32 v163, 0xffff0000, v108
	v_lshlrev_b32_e32 v108, 16, v109
	v_and_b32_e32 v109, 0xffff0000, v109
	v_pk_add_f32 v[104:105], v[104:105], v[108:109]
	v_pk_add_f32 v[108:109], v[164:165], v[162:163]
	s_waitcnt vmcnt(11)
	v_lshlrev_b32_e32 v162, 16, v110
	v_and_b32_e32 v163, 0xffff0000, v110
	v_lshlrev_b32_e32 v110, 16, v111
	v_and_b32_e32 v111, 0xffff0000, v111
	v_pk_add_f32 v[102:103], v[102:103], v[110:111]
	v_lshlrev_b32_e32 v110, 16, v112
	v_and_b32_e32 v111, 0xffff0000, v112
	v_lshlrev_b32_e32 v112, 16, v113
	v_and_b32_e32 v113, 0xffff0000, v113
	v_pk_add_f32 v[106:107], v[106:107], v[162:163]
	v_pk_add_f32 v[108:109], v[108:109], v[110:111]
	v_pk_add_f32 v[104:105], v[104:105], v[112:113]
	s_waitcnt vmcnt(9)
	v_lshlrev_b32_e32 v110, 16, v114
	v_and_b32_e32 v111, 0xffff0000, v114
	v_lshlrev_b32_e32 v112, 16, v115
	v_and_b32_e32 v113, 0xffff0000, v115
	v_pk_add_f32 v[102:103], v[102:103], v[112:113]
	v_pk_add_f32 v[106:107], v[106:107], v[110:111]
	v_lshlrev_b32_e32 v110, 16, v116
	v_and_b32_e32 v111, 0xffff0000, v116
	v_lshlrev_b32_e32 v112, 16, v117
	v_and_b32_e32 v113, 0xffff0000, v117
	v_pk_add_f32 v[104:105], v[104:105], v[112:113]
	v_pk_add_f32 v[108:109], v[108:109], v[110:111]
	s_waitcnt vmcnt(7)
	v_lshlrev_b32_e32 v110, 16, v118
	v_and_b32_e32 v111, 0xffff0000, v118
	v_lshlrev_b32_e32 v112, 16, v119
	v_and_b32_e32 v113, 0xffff0000, v119
	v_pk_add_f32 v[106:107], v[106:107], v[110:111]
	v_pk_add_f32 v[102:103], v[102:103], v[112:113]
	v_lshlrev_b32_e32 v110, 16, v120
	v_and_b32_e32 v111, 0xffff0000, v120
	v_lshlrev_b32_e32 v112, 16, v121
	v_and_b32_e32 v113, 0xffff0000, v121
	v_pk_add_f32 v[108:109], v[108:109], v[110:111]
	v_pk_add_f32 v[104:105], v[104:105], v[112:113]
	s_waitcnt vmcnt(5)
	v_lshlrev_b32_e32 v110, 16, v122
	v_and_b32_e32 v111, 0xffff0000, v122
	v_lshlrev_b32_e32 v112, 16, v123
	v_and_b32_e32 v113, 0xffff0000, v123
	v_pk_add_f32 v[102:103], v[102:103], v[112:113]
	v_pk_add_f32 v[106:107], v[106:107], v[110:111]
	v_lshlrev_b32_e32 v110, 16, v124
	v_and_b32_e32 v111, 0xffff0000, v124
	v_lshlrev_b32_e32 v112, 16, v125
	v_and_b32_e32 v113, 0xffff0000, v125
	v_pk_add_f32 v[104:105], v[104:105], v[112:113]
	v_pk_add_f32 v[108:109], v[108:109], v[110:111]
	s_waitcnt vmcnt(3)
	v_lshlrev_b32_e32 v110, 16, v126
	v_and_b32_e32 v111, 0xffff0000, v126
	v_lshlrev_b32_e32 v112, 16, v127
	v_and_b32_e32 v113, 0xffff0000, v127
	v_pk_add_f32 v[106:107], v[106:107], v[110:111]
	v_pk_add_f32 v[102:103], v[102:103], v[112:113]
	v_lshlrev_b32_e32 v110, 16, v128
	v_and_b32_e32 v111, 0xffff0000, v128
	v_lshlrev_b32_e32 v112, 16, v129
	v_and_b32_e32 v113, 0xffff0000, v129
	v_pk_add_f32 v[108:109], v[108:109], v[110:111]
	v_pk_add_f32 v[104:105], v[104:105], v[112:113]
	s_waitcnt vmcnt(1)
	v_lshlrev_b32_e32 v110, 16, v156
	v_and_b32_e32 v111, 0xffff0000, v156
	v_lshlrev_b32_e32 v112, 16, v157
	v_and_b32_e32 v113, 0xffff0000, v157
	v_pk_add_f32 v[102:103], v[102:103], v[112:113]
	v_pk_add_f32 v[106:107], v[106:107], v[110:111]
	v_lshlrev_b32_e32 v110, 16, v158
	v_and_b32_e32 v111, 0xffff0000, v158
	v_lshlrev_b32_e32 v112, 16, v159
	v_and_b32_e32 v113, 0xffff0000, v159
	v_pk_add_f32 v[112:113], v[104:105], v[112:113]
	v_pk_add_f32 v[108:109], v[108:109], v[110:111]
	v_cvt_pk_bf16_f32 v105, v102, v103
	v_lshlrev_b64 v[102:103], 12, v[160:161]
	v_cvt_pk_bf16_f32 v104, v106, v107
	v_cvt_pk_bf16_f32 v106, v108, v109
	v_lshl_add_u64 v[108:109], s[40:41], 0, v[102:103]
	v_cvt_pk_bf16_f32 v107, v112, v113
	v_lshl_add_u64 v[108:109], v[146:147], 1, v[108:109]
	global_store_dwordx4 v[108:109], v[104:107], off
	v_lshlrev_b32_e32 v108, 16, v94
	v_and_b32_e32 v109, 0xffff0000, v94
	v_lshlrev_b32_e32 v104, 16, v98
	v_and_b32_e32 v105, 0xffff0000, v98
	v_lshlrev_b32_e32 v98, 16, v99
	v_and_b32_e32 v99, 0xffff0000, v99
	v_pk_add_f32 v[104:105], v[104:105], 0 op_sel_hi:[1,0]
	v_pk_add_f32 v[98:99], v[98:99], 0 op_sel_hi:[1,0]
	v_lshlrev_b32_e32 v106, 16, v100
	v_and_b32_e32 v107, 0xffff0000, v100
	v_lshlrev_b32_e32 v100, 16, v101
	v_and_b32_e32 v101, 0xffff0000, v101
	v_lshlrev_b32_e32 v94, 16, v95
	v_and_b32_e32 v95, 0xffff0000, v95
	v_pk_add_f32 v[106:107], v[106:107], 0 op_sel_hi:[1,0]
	v_pk_add_f32 v[100:101], v[100:101], 0 op_sel_hi:[1,0]
	v_pk_add_f32 v[94:95], v[98:99], v[94:95]
	v_pk_add_f32 v[98:99], v[104:105], v[108:109]
	v_lshlrev_b32_e32 v104, 16, v96
	v_and_b32_e32 v105, 0xffff0000, v96
	v_lshlrev_b32_e32 v96, 16, v97
	v_and_b32_e32 v97, 0xffff0000, v97
	v_pk_add_f32 v[96:97], v[100:101], v[96:97]
	v_pk_add_f32 v[100:101], v[106:107], v[104:105]
	v_lshlrev_b32_e32 v104, 16, v90
	v_and_b32_e32 v105, 0xffff0000, v90
	v_lshlrev_b32_e32 v90, 16, v91
	v_and_b32_e32 v91, 0xffff0000, v91
	v_pk_add_f32 v[90:91], v[94:95], v[90:91]
	v_lshlrev_b32_e32 v94, 16, v92
	v_and_b32_e32 v95, 0xffff0000, v92
	v_lshlrev_b32_e32 v92, 16, v93
	v_and_b32_e32 v93, 0xffff0000, v93
	v_pk_add_f32 v[98:99], v[98:99], v[104:105]
	v_pk_add_f32 v[92:93], v[96:97], v[92:93]
	v_lshlrev_b32_e32 v96, 16, v86
	v_and_b32_e32 v97, 0xffff0000, v86
	v_lshlrev_b32_e32 v86, 16, v87
	v_and_b32_e32 v87, 0xffff0000, v87
	v_pk_add_f32 v[94:95], v[100:101], v[94:95]
	v_pk_add_f32 v[86:87], v[90:91], v[86:87]
	v_pk_add_f32 v[90:91], v[98:99], v[96:97]
	v_lshlrev_b32_e32 v96, 16, v88
	v_and_b32_e32 v97, 0xffff0000, v88
	v_lshlrev_b32_e32 v88, 16, v89
	v_and_b32_e32 v89, 0xffff0000, v89
	v_pk_add_f32 v[88:89], v[92:93], v[88:89]
	v_pk_add_f32 v[92:93], v[94:95], v[96:97]
	v_lshlrev_b32_e32 v94, 16, v82
	v_and_b32_e32 v95, 0xffff0000, v82
	v_lshlrev_b32_e32 v82, 16, v83
	v_and_b32_e32 v83, 0xffff0000, v83
	v_pk_add_f32 v[82:83], v[86:87], v[82:83]
	v_lshlrev_b32_e32 v86, 16, v84
	v_and_b32_e32 v87, 0xffff0000, v84
	v_lshlrev_b32_e32 v84, 16, v85
	v_and_b32_e32 v85, 0xffff0000, v85
	v_pk_add_f32 v[90:91], v[90:91], v[94:95]
	v_pk_add_f32 v[84:85], v[88:89], v[84:85]
	v_lshlrev_b32_e32 v88, 16, v78
	v_and_b32_e32 v89, 0xffff0000, v78
	v_lshlrev_b32_e32 v78, 16, v79
	v_and_b32_e32 v79, 0xffff0000, v79
	v_pk_add_f32 v[86:87], v[92:93], v[86:87]
	v_pk_add_f32 v[78:79], v[82:83], v[78:79]
	v_pk_add_f32 v[82:83], v[90:91], v[88:89]
	v_lshlrev_b32_e32 v88, 16, v80
	v_and_b32_e32 v89, 0xffff0000, v80
	v_lshlrev_b32_e32 v80, 16, v81
	v_and_b32_e32 v81, 0xffff0000, v81
	v_pk_add_f32 v[80:81], v[84:85], v[80:81]
	v_pk_add_f32 v[84:85], v[86:87], v[88:89]
	v_lshlrev_b32_e32 v86, 16, v74
	v_and_b32_e32 v87, 0xffff0000, v74
	v_lshlrev_b32_e32 v74, 16, v75
	v_and_b32_e32 v75, 0xffff0000, v75
	v_pk_add_f32 v[74:75], v[78:79], v[74:75]
	v_lshlrev_b32_e32 v78, 16, v76
	v_and_b32_e32 v79, 0xffff0000, v76
	v_lshlrev_b32_e32 v76, 16, v77
	v_and_b32_e32 v77, 0xffff0000, v77
	v_pk_add_f32 v[78:79], v[84:85], v[78:79]
	s_waitcnt vmcnt(1)
	v_lshlrev_b32_e32 v84, 16, v70
	v_and_b32_e32 v85, 0xffff0000, v70
	v_lshlrev_b32_e32 v70, 16, v71
	v_and_b32_e32 v71, 0xffff0000, v71
	v_pk_add_f32 v[82:83], v[82:83], v[86:87]
	v_pk_add_f32 v[80:81], v[80:81], v[76:77]
	v_pk_add_f32 v[76:77], v[74:75], v[70:71]
	v_lshlrev_b32_e32 v70, 16, v72
	v_and_b32_e32 v71, 0xffff0000, v72
	v_lshlrev_b32_e32 v72, 16, v73
	v_and_b32_e32 v73, 0xffff0000, v73
	v_pk_add_f32 v[74:75], v[82:83], v[84:85]
	v_pk_add_f32 v[72:73], v[80:81], v[72:73]
	v_pk_add_f32 v[70:71], v[78:79], v[70:71]

.LBB0_1249:
	s_ashr_i32 s0, s3, 3
	s_add_i32 s0, s8, s0
	s_ashr_i32 s8, s0, 31
	s_lshr_b32 s8, s8, 26
	s_add_i32 s8, s0, s8
	s_ashr_i32 s9, s8, 6
	s_andn2_b32 s8, s8, 63
	s_sub_i32 s8, s0, s8
	s_waitcnt vmcnt(0)
	v_lshrrev_b32_e32 v3, 1, v143
	s_bfe_i32 s0, s8, 0x80000
	v_and_b32_e32 v15, 24, v3
	v_lshrrev_b32_e32 v3, 5, v143
	s_bfe_u32 s0, s0, 0x3000c
	v_and_b32_e32 v3, 4, v3
	v_bfe_u32 v4, v143, 2, 2
	s_add_i32 s10, s8, s0
	v_lshlrev_b32_e32 v2, 4, v143
	v_and_b32_e32 v1, 32, v143
	v_bfe_u32 v14, v143, 2, 4
	v_or3_b32 v3, v3, v4, v15
	v_lshrrev_b32_e32 v4, 3, v143
	s_movk_i32 s3, 0x70
	s_bfe_i32 s0, s10, 0x80000
	s_and_b32 s10, s10, 0xf8
	v_bitop3_b32 v12, v2, v1, 48 bitop3:0x6c
	v_and_b32_e32 v13, 64, v143
	v_and_or_b32 v5, v4, s3, v14
	s_movk_i32 s3, 0x60
	s_sub_i32 s8, s8, s10
	v_or_b32_e32 v1, v12, v13
	v_and_or_b32 v4, v4, s3, v3
	v_add_u32_e32 v16, 0x2000, v2
	s_lshl_b32 s9, s9, 3
	s_sext_i32_i16 s0, s0
	s_sext_i32_i8 s8, s8
	s_lshr_b32 s1, s4, 8
	v_lshl_or_b32 v132, v4, 12, v1
	v_lshrrev_b32_e32 v4, 7, v16
	s_movk_i32 s3, 0xf0
	s_lshr_b32 s0, s0, 3
	s_add_i32 s8, s9, s8
	v_lshl_or_b32 v130, v5, 12, v1
	v_and_or_b32 v5, v4, s3, v14
	s_movk_i32 s3, 0xe0
	s_lshr_b32 s5, s4, 6
	s_ashr_i32 s9, s8, 31
	s_bfe_i64 s[12:13], s[0:1], 0x100000
	v_and_or_b32 v3, v4, s3, v3
	s_lshl_b32 s3, s5, 10
	s_lshl_b64 s[10:11], s[8:9], 20
	s_lshl_b64 s[12:13], s[12:13], 20
	v_readlane_b32 s14, v242, 49
	v_readlane_b32 s15, v242, 50
	s_add_u32 s36, s14, s12
	s_addc_u32 s37, s15, s13
	s_add_i32 s42, s3, 0
	s_add_i32 m0, s42, 0x10000
	v_lshl_or_b32 v136, v3, 12, v1
	v_mov_b32_e32 v253, 0xa100
	global_load_dword v253, v253, s[70:71] sc1
	global_load_lds_dwordx4 v132, s[36:37]
	s_add_i32 m0, s42, 0x12000
	s_add_u32 s12, s36, 0x80000
	global_load_lds_dwordx4 v136, s[36:37]
	s_addc_u32 s13, s37, 0
	s_add_i32 m0, s42, 0x14000
	v_lshl_or_b32 v134, v5, 12, v1
	global_load_lds_dwordx4 v132, s[12:13]
	s_add_i32 m0, s42, 0x16000
	s_add_u32 s48, s44, s10
	s_addc_u32 s49, s45, s11
	s_add_i32 s43, s42, 0x2000
	global_load_lds_dwordx4 v136, s[12:13]
	s_mov_b32 m0, s42
	s_add_u32 s10, s48, 0x80000
	global_load_lds_dwordx4 v130, s[48:49]
	s_mov_b32 m0, s43
	s_addc_u32 s11, s49, 0
	s_add_i32 s58, s42, 0x4000
	global_load_lds_dwordx4 v134, s[48:49]
	s_mov_b32 m0, s58
	s_add_i32 s59, s42, 0x6000
	global_load_lds_dwordx4 v130, s[10:11]
	s_mov_b32 m0, s59
	v_mov_b32_e32 v133, 0
	global_load_lds_dwordx4 v134, s[10:11]
	v_mov_b32_e32 v137, v133
	v_mov_b32_e32 v131, v133
	v_mov_b32_e32 v135, v133
	s_cmp_eq_u32 s1, 1
	s_mov_b32 s54, 32
	s_mov_b32 s9, 0
	v_lshl_add_u64 v[10:11], s[36:37], 0, v[132:133]
	v_lshl_add_u64 v[8:9], s[36:37], 0, v[136:137]
	v_lshl_add_u64 v[6:7], s[48:49], 0, v[130:131]
	s_cselect_b64 s[10:11], -1, 0
	s_cmp_lg_u32 s1, 1
	v_lshl_add_u64 v[4:5], s[48:49], 0, v[134:135]
	s_cbranch_scc1 .LBB0_1251
	s_barrier
.LBB0_1251:
	s_add_u32 s60, s70, 0x12000
	s_addc_u32 s61, s71, 0
	s_lshl_b32 s5, s5, 5
	s_mov_b64 s[12:13], 0x80
	s_and_b32 s5, s5, 0x60
	s_add_i32 m0, s42, 0x18000
	v_lshl_add_u64 v[10:11], v[10:11], 0, s[12:13]
	s_lshl_b32 s16, s1, 13
	s_lshl_b32 s17, s5, 7
	s_waitcnt vmcnt(2)
	s_barrier
	global_load_lds_dwordx4 v[10:11], off
	v_lshl_add_u64 v[8:9], v[8:9], 0, s[12:13]
	s_add_i32 m0, s42, 0x1a000
	s_add_i32 s62, s42, 0x8000
	s_add_i32 s63, s42, 0xa000
	global_load_lds_dwordx4 v[8:9], off
	v_lshl_add_u64 v[6:7], v[6:7], 0, s[12:13]
	s_mov_b32 m0, s62
	s_add_u32 s14, s36, 0x80080
	global_load_lds_dwordx4 v[6:7], off
	v_lshl_add_u64 v[4:5], v[4:5], 0, s[12:13]
	s_mov_b32 m0, s63
	s_addc_u32 s15, s37, 0
	global_load_lds_dwordx4 v[4:5], off
	s_add_i32 m0, s42, 0x1c000
	v_lshl_add_u64 v[4:5], s[14:15], 0, v[132:133]
	global_load_lds_dwordx4 v[4:5], off
	v_lshl_add_u64 v[4:5], s[14:15], 0, v[136:137]
	s_add_i32 m0, s42, 0x1e000
	v_and_b32_e32 v3, 15, v143
	global_load_lds_dwordx4 v[4:5], off
	v_lshlrev_b32_e32 v4, 1, v15
	v_lshlrev_b32_e32 v5, 2, v143
	v_lshl_or_b32 v1, s1, 6, v3
	v_lshl_or_b32 v3, v3, 6, v4
	v_and_b32_e32 v5, 32, v5
	s_sext_i32_i8 s55, s0
	v_bitop3_b32 v6, v3, s16, v5 bitop3:0xde
	v_lshlrev_b32_e32 v3, 6, v143
	s_movk_i32 s0, 0x3c0
	v_and_or_b32 v3, v3, s0, v4
	v_readlane_b32 s18, v242, 53
	v_bitop3_b32 v150, s17, v3, v5 bitop3:0xf6
	v_mov_b32_e32 v3, v133
	v_readlane_b32 s19, v242, 54
	s_cmpk_lt_u32 s4, 0x100
	s_waitcnt vmcnt(6)
	s_cselect_b64 s[14:15], -1, 0
	v_lshl_add_u64 v[138:139], s[18:19], 0, v[2:3]
	v_lshlrev_b32_e32 v2, 9, v143
	v_and_b32_e32 v2, 0x70000, v2
	v_lshlrev_b32_e32 v3, 12, v14
	v_or3_b32 v2, v12, v2, v3
	v_add_u32_e32 v140, v2, v13
	v_lshlrev_b32_e32 v2, 5, v16
	s_cmpk_lt_i32 s2, 0x80
	v_and_b32_e32 v2, 0xf0000, v2
	s_cselect_b64 s[16:17], -1, 0
	s_ashr_i32 s66, s2, 3
	s_and_b32 s67, s2, 7
	v_readfirstlane_b32 s98, v253
	s_cmp_eq_u32 s98, 0
	s_cbranch_scc0 .Lxs_slow_11
	s_lshr_b32 s99, s2, 6
	s_lshl_b32 s99, s99, 3
	s_and_b32 s100, s2, 7
	s_or_b32 s66, s99, s100
	s_bfe_u32 s67, s2, 0x30003
.Lxs_slow_11:
	s_ashr_i32 s4, s2, 6
	v_or3_b32 v2, v12, v2, v3
	s_add_i32 s76, 0, 0x10000
	s_add_i32 s77, 0, 0x14000
	v_cmp_eq_u32_e64 s[0:1], 0, v143
	s_add_i32 s18, s4, 32
	s_and_b32 s20, s66, 7
	s_lshl_b32 s22, s67, 2
	v_or_b32_e32 v151, s5, v15
	v_mov_b32_e32 v141, v133
	v_add_u32_e32 v144, v2, v13
	v_mov_b32_e32 v145, v133
	s_mov_b64 s[4:5], -1
	s_mov_b32 s81, -1
	v_add_u32_e32 v152, s76, v150
	v_add_u32_e32 v153, s77, v150
	v_add_u32_e32 v154, 0, v6
	s_mov_b32 s78, 0x80000
	s_mov_b32 s79, 0xa0000
	s_mov_b64 s[24:25], 0x90000
	s_mov_b32 s80, 0x90000
	s_mov_b64 s[26:27], 0xa0000
	s_mov_b64 s[28:29], 0xb0000
	s_mov_b32 s56, 0
	s_barrier
	s_branch .LBB0_1254

.LBB0_1262:
	v_lshl_add_u32 v148, s8, 8, v1
	v_lshl_or_b32 v146, s55, 8, v151
	s_mov_b64 s[36:37], -1
	s_cmp_gt_i32 s81, -1
	v_cvt_pk_bf16_f32 v66, v66, v67
	v_cvt_pk_bf16_f32 v67, v68, v69
	v_cvt_pk_bf16_f32 v68, v126, v127
	v_cvt_pk_bf16_f32 v69, v128, v129
	v_cvt_pk_bf16_f32 v62, v62, v63
	v_cvt_pk_bf16_f32 v63, v64, v65
	v_cvt_pk_bf16_f32 v64, v58, v59
	v_cvt_pk_bf16_f32 v65, v60, v61
	v_cvt_pk_bf16_f32 v58, v122, v123
	v_cvt_pk_bf16_f32 v59, v124, v125
	v_cvt_pk_bf16_f32 v60, v118, v119
	v_cvt_pk_bf16_f32 v61, v120, v121
	v_cvt_pk_bf16_f32 v54, v54, v55
	v_cvt_pk_bf16_f32 v55, v56, v57
	v_cvt_pk_bf16_f32 v56, v50, v51
	v_cvt_pk_bf16_f32 v57, v52, v53
	v_cvt_pk_bf16_f32 v50, v114, v115
	v_cvt_pk_bf16_f32 v51, v116, v117
	v_cvt_pk_bf16_f32 v52, v110, v111
	v_cvt_pk_bf16_f32 v53, v112, v113
	v_cvt_pk_bf16_f32 v46, v46, v47
	v_cvt_pk_bf16_f32 v47, v48, v49
	v_cvt_pk_bf16_f32 v48, v42, v43
	v_cvt_pk_bf16_f32 v49, v44, v45
	v_cvt_pk_bf16_f32 v42, v106, v107
	v_cvt_pk_bf16_f32 v43, v108, v109
	v_cvt_pk_bf16_f32 v44, v102, v103
	v_cvt_pk_bf16_f32 v45, v104, v105
	v_cvt_pk_bf16_f32 v38, v38, v39
	v_cvt_pk_bf16_f32 v39, v40, v41
	v_cvt_pk_bf16_f32 v40, v98, v99
	v_cvt_pk_bf16_f32 v41, v100, v101
	v_cvt_pk_bf16_f32 v34, v34, v35
	v_cvt_pk_bf16_f32 v35, v36, v37
	v_cvt_pk_bf16_f32 v36, v94, v95
	v_cvt_pk_bf16_f32 v37, v96, v97
	v_cvt_pk_bf16_f32 v30, v30, v31
	v_cvt_pk_bf16_f32 v31, v32, v33
	v_cvt_pk_bf16_f32 v32, v26, v27
	v_cvt_pk_bf16_f32 v33, v28, v29
	v_cvt_pk_bf16_f32 v26, v90, v91
	v_cvt_pk_bf16_f32 v27, v92, v93
	v_cvt_pk_bf16_f32 v28, v86, v87
	v_cvt_pk_bf16_f32 v29, v88, v89
	v_cvt_pk_bf16_f32 v22, v22, v23
	v_cvt_pk_bf16_f32 v23, v24, v25
	v_cvt_pk_bf16_f32 v24, v18, v19
	v_cvt_pk_bf16_f32 v25, v20, v21
	v_cvt_pk_bf16_f32 v18, v82, v83
	v_cvt_pk_bf16_f32 v19, v84, v85
	v_cvt_pk_bf16_f32 v20, v78, v79
	v_cvt_pk_bf16_f32 v21, v80, v81
	v_cvt_pk_bf16_f32 v14, v14, v15
	v_cvt_pk_bf16_f32 v15, v16, v17
	v_cvt_pk_bf16_f32 v16, v10, v11
	v_cvt_pk_bf16_f32 v17, v12, v13
	v_cvt_pk_bf16_f32 v10, v74, v75
	v_cvt_pk_bf16_f32 v11, v76, v77
	v_cvt_pk_bf16_f32 v12, v70, v71
	v_cvt_pk_bf16_f32 v13, v72, v73
	s_cbranch_scc0 .LBB0_1276
	s_lshl_b32 s36, s56, 3
	s_add_i32 s48, s36, s81
	s_ashr_i32 s49, s48, 31
	s_lshl_b64 s[48:49], s[48:49], 17
	v_lshl_add_u64 v[74:75], v[138:139], 0, s[48:49]
	s_movk_i32 s8, 0x2000
	v_add_co_u32_e32 v70, vcc, s8, v74
	s_movk_i32 s8, 0x4000
	s_nop 0
	v_addc_co_u32_e32 v71, vcc, 0, v75, vcc
	global_store_dwordx4 v[70:71], v[62:65], off
	v_add_co_u32_e32 v70, vcc, s8, v74
	s_movk_i32 s8, 0x6000
	s_nop 0
	v_addc_co_u32_e32 v71, vcc, 0, v75, vcc
	global_store_dwordx4 v[70:71], v[58:61], off
	v_add_co_u32_e32 v70, vcc, s8, v74
	s_mov_b32 s8, 0x8000
	s_nop 0
	v_addc_co_u32_e32 v71, vcc, 0, v75, vcc
	global_store_dwordx4 v[70:71], v[54:57], off
	v_add_co_u32_e32 v70, vcc, s8, v74
	s_mov_b32 s8, 0xa000
	s_nop 0
	v_addc_co_u32_e32 v71, vcc, 0, v75, vcc
	global_store_dwordx4 v[70:71], v[50:53], off
	v_add_co_u32_e32 v70, vcc, s8, v74
	s_mov_b32 s8, 0xc000
	s_nop 0
	v_addc_co_u32_e32 v71, vcc, 0, v75, vcc
	global_store_dwordx4 v[70:71], v[46:49], off
	v_add_co_u32_e32 v70, vcc, s8, v74
	s_mov_b32 s8, 0xe000
	s_nop 0
	v_addc_co_u32_e32 v71, vcc, 0, v75, vcc
	global_store_dwordx4 v[70:71], v[42:45], off
	v_add_co_u32_e32 v70, vcc, s8, v74
	s_mov_b32 s8, 0x10000
	s_nop 0
	v_addc_co_u32_e32 v71, vcc, 0, v75, vcc
	global_store_dwordx4 v[70:71], v[38:41], off
	v_add_co_u32_e32 v70, vcc, s8, v74
	s_mov_b32 s8, 0x12000
	s_nop 0
	v_addc_co_u32_e32 v71, vcc, 0, v75, vcc
	global_store_dwordx4 v[70:71], v[34:37], off
	v_add_co_u32_e32 v70, vcc, s8, v74
	s_mov_b32 s8, 0x14000
	s_nop 0
	v_addc_co_u32_e32 v71, vcc, 0, v75, vcc
	global_store_dwordx4 v[70:71], v[30:33], off
	v_add_co_u32_e32 v70, vcc, s8, v74
	s_mov_b32 s8, 0x16000
	s_nop 0
	v_addc_co_u32_e32 v71, vcc, 0, v75, vcc
	global_store_dwordx4 v[70:71], v[26:29], off
	v_add_co_u32_e32 v70, vcc, s8, v74
	s_mov_b32 s8, 0x18000
	s_nop 0
	v_addc_co_u32_e32 v71, vcc, 0, v75, vcc
	global_store_dwordx4 v[70:71], v[22:25], off
	v_add_co_u32_e32 v70, vcc, s8, v74
	s_mov_b32 s8, 0x1a000
	s_nop 0
	v_addc_co_u32_e32 v71, vcc, 0, v75, vcc
	global_store_dwordx4 v[70:71], v[18:21], off
	v_add_co_u32_e32 v70, vcc, s8, v74
	s_mov_b32 s8, 0x1c000
	s_nop 0
	v_addc_co_u32_e32 v71, vcc, 0, v75, vcc
	global_store_dwordx4 v[70:71], v[14:17], off
	v_add_co_u32_e32 v70, vcc, s8, v74
	global_store_dwordx4 v[74:75], v[66:69], off
	s_nop 0
	v_addc_co_u32_e32 v71, vcc, 0, v75, vcc
	v_add_co_u32_e32 v74, vcc, 0x1e000, v74
	global_store_dwordx4 v[70:71], v[10:13], off
	v_cvt_pk_bf16_f32 v70, v6, v7
	v_cvt_pk_bf16_f32 v71, v8, v9
	v_cvt_pk_bf16_f32 v72, v2, v3
	v_cvt_pk_bf16_f32 v73, v4, v5
	v_addc_co_u32_e32 v75, vcc, 0, v75, vcc
	global_store_dwordx4 v[74:75], v[70:73], off
	s_waitcnt vmcnt(0)
	s_waitcnt vmcnt(0)
	s_barrier
	s_and_saveexec_b64 s[48:49], s[0:1]
	s_cbranch_execz .LBB0_1275
	s_lshl_b32 s50, s56, 6
	s_mov_b64 s[54:55], exec
	s_ashr_i32 s51, s50, 31
	s_lshl_b64 s[50:51], s[50:51], 2
	s_cmp_eq_u32 s98, 0
	s_cbranch_scc1 .Lxs_nowb_11
	buffer_wbl2 sc1
.Lxs_nowb_11:
	s_waitcnt vmcnt(0)
	v_mbcnt_lo_u32_b32 v70, s54, 0
	s_add_u32 s50, s60, s50
	v_mbcnt_hi_u32_b32 v70, s55, v70
	s_addc_u32 s51, s61, s51
	v_cmp_eq_u32_e32 vcc, 0, v70
	s_and_saveexec_b64 s[56:57], vcc
	s_cbranch_execz .LBB0_1266
	s_bcnt1_i32_b64 s8, s[54:55]
	v_mov_b32_e32 v70, s8
	global_atomic_add v133, v70, s[50:51]

.LBB0_1275:
	s_or_b64 exec, exec, s[48:49]
	s_ashr_i32 s37, s36, 31
	s_lshl_b64 s[36:37], s[36:37], 17
	s_lshl_b32 s8, s81, 1
	v_lshl_add_u64 v[70:71], v[138:139], 0, s[36:37]
	s_lshl_b64 s[36:37], s[8:9], 13
	v_lshl_add_u64 v[70:71], v[70:71], 0, s[36:37]
	v_add_co_u32_e32 v72, vcc, 0x2000, v70
	s_nop 1
	v_addc_co_u32_e32 v73, vcc, 0, v71, vcc
	s_barrier
	global_load_dwordx4 v[102:105], v[70:71], off sc0
	global_load_dwordx4 v[98:101], v[72:73], off sc0
	v_add_co_u32_e32 v72, vcc, 0x20000, v70
	s_lshl_b32 s8, s81, 5
	s_nop 0
	v_addc_co_u32_e32 v73, vcc, 0, v71, vcc
	v_add_co_u32_e32 v74, vcc, 0x22000, v70
	s_and_b32 s8, s8, 0x7fffff80
	s_nop 0
	v_addc_co_u32_e32 v75, vcc, 0, v71, vcc
	global_load_dwordx4 v[106:109], v[72:73], off sc0
	global_load_dwordx4 v[94:97], v[74:75], off sc0
	v_add_co_u32_e32 v72, vcc, 0x40000, v70
	v_add_u32_e32 v147, s8, v148
	s_nop 0
	v_addc_co_u32_e32 v73, vcc, 0, v71, vcc
	v_add_co_u32_e32 v74, vcc, 0x42000, v70
	s_lshl_b32 s8, s81, 4
	s_nop 0
	v_addc_co_u32_e32 v75, vcc, 0, v71, vcc
	global_load_dwordx4 v[110:113], v[72:73], off sc0
	global_load_dwordx4 v[90:93], v[74:75], off sc0
	v_add_co_u32_e32 v72, vcc, 0x60000, v70
	v_and_or_b32 v160, s8, 48, v147
	s_nop 0
	v_addc_co_u32_e32 v73, vcc, 0, v71, vcc
	v_add_co_u32_e32 v74, vcc, 0x62000, v70
	v_ashrrev_i32_e32 v161, 31, v160
	s_nop 0
	v_addc_co_u32_e32 v75, vcc, 0, v71, vcc
	global_load_dwordx4 v[114:117], v[72:73], off sc0
	global_load_dwordx4 v[86:89], v[74:75], off sc0
	v_add_co_u32_e32 v72, vcc, 0x80000, v70
	v_ashrrev_i32_e32 v147, 31, v146
	s_nop 0
	v_addc_co_u32_e32 v73, vcc, 0, v71, vcc
	v_add_co_u32_e32 v74, vcc, 0x82000, v70
	s_mov_b64 s[36:37], 0
	s_nop 0
	v_addc_co_u32_e32 v75, vcc, 0, v71, vcc
	global_load_dwordx4 v[118:121], v[72:73], off sc0
	global_load_dwordx4 v[82:85], v[74:75], off sc0
	v_add_co_u32_e32 v72, vcc, 0xa0000, v70
	s_waitcnt vmcnt(9)
	v_lshlrev_b32_e32 v162, 16, v102
	v_addc_co_u32_e32 v73, vcc, 0, v71, vcc
	v_add_co_u32_e32 v74, vcc, 0xa2000, v70
	v_and_b32_e32 v163, 0xffff0000, v102
	s_nop 0
	v_addc_co_u32_e32 v75, vcc, 0, v71, vcc
	global_load_dwordx4 v[122:125], v[72:73], off sc0
	global_load_dwordx4 v[78:81], v[74:75], off sc0
	v_add_co_u32_e32 v72, vcc, 0xc0000, v70
	v_lshlrev_b32_e32 v102, 16, v103
	s_nop 0
	v_addc_co_u32_e32 v73, vcc, 0, v71, vcc
	v_add_co_u32_e32 v74, vcc, 0xc2000, v70
	v_and_b32_e32 v103, 0xffff0000, v103
	s_nop 0
	v_addc_co_u32_e32 v75, vcc, 0, v71, vcc
	global_load_dwordx4 v[126:129], v[72:73], off sc0
	s_nop 0
	global_load_dwordx4 v[74:77], v[74:75], off sc0
	v_add_co_u32_e32 v72, vcc, 0xe0000, v70
	v_pk_add_f32 v[162:163], v[162:163], 0 op_sel_hi:[1,0]
	s_nop 0
	v_addc_co_u32_e32 v73, vcc, 0, v71, vcc
	v_add_co_u32_e32 v70, vcc, 0xe2000, v70
	v_pk_add_f32 v[102:103], v[102:103], 0 op_sel_hi:[1,0]
	s_nop 0
	v_addc_co_u32_e32 v71, vcc, 0, v71, vcc
	global_load_dwordx4 v[156:159], v[72:73], off sc0
	s_nop 0
	global_load_dwordx4 v[70:73], v[70:71], off sc0
	v_lshlrev_b32_e32 v164, 16, v104
	v_and_b32_e32 v165, 0xffff0000, v104
	v_lshlrev_b32_e32 v104, 16, v105
	v_and_b32_e32 v105, 0xffff0000, v105
	s_waitcnt vmcnt(13)
	v_lshlrev_b32_e32 v166, 16, v106
	v_and_b32_e32 v167, 0xffff0000, v106
	v_lshlrev_b32_e32 v106, 16, v107
	v_and_b32_e32 v107, 0xffff0000, v107
	v_pk_add_f32 v[164:165], v[164:165], 0 op_sel_hi:[1,0]
	v_pk_add_f32 v[104:105], v[104:105], 0 op_sel_hi:[1,0]
	v_pk_add_f32 v[102:103], v[102:103], v[106:107]
	v_pk_add_f32 v[106:107], v[162:163], v[166:167]
	v_lshlrev_b32_e32 v162, 16, v108
	v_and_b32_e32 v163, 0xffff0000, v108
	v_lshlrev_b32_e32 v108, 16, v109
	v_and_b32_e32 v109, 0xffff0000, v109
	v_pk_add_f32 v[104:105], v[104:105], v[108:109]
	v_pk_add_f32 v[108:109], v[164:165], v[162:163]
	s_waitcnt vmcnt(11)
	v_lshlrev_b32_e32 v162, 16, v110
	v_and_b32_e32 v163, 0xffff0000, v110
	v_lshlrev_b32_e32 v110, 16, v111
	v_and_b32_e32 v111, 0xffff0000, v111
	v_pk_add_f32 v[102:103], v[102:103], v[110:111]
	v_lshlrev_b32_e32 v110, 16, v112
	v_and_b32_e32 v111, 0xffff0000, v112
	v_lshlrev_b32_e32 v112, 16, v113
	v_and_b32_e32 v113, 0xffff0000, v113
	v_pk_add_f32 v[106:107], v[106:107], v[162:163]
	v_pk_add_f32 v[108:109], v[108:109], v[110:111]
	v_pk_add_f32 v[104:105], v[104:105], v[112:113]
	s_waitcnt vmcnt(9)
	v_lshlrev_b32_e32 v110, 16, v114
	v_and_b32_e32 v111, 0xffff0000, v114
	v_lshlrev_b32_e32 v112, 16, v115
	v_and_b32_e32 v113, 0xffff0000, v115
	v_pk_add_f32 v[102:103], v[102:103], v[112:113]
	v_pk_add_f32 v[106:107], v[106:107], v[110:111]
	v_lshlrev_b32_e32 v110, 16, v116
	v_and_b32_e32 v111, 0xffff0000, v116
	v_lshlrev_b32_e32 v112, 16, v117
	v_and_b32_e32 v113, 0xffff0000, v117
	v_pk_add_f32 v[104:105], v[104:105], v[112:113]
	v_pk_add_f32 v[108:109], v[108:109], v[110:111]
	s_waitcnt vmcnt(7)
	v_lshlrev_b32_e32 v110, 16, v118
	v_and_b32_e32 v111, 0xffff0000, v118
	v_lshlrev_b32_e32 v112, 16, v119
	v_and_b32_e32 v113, 0xffff0000, v119
	v_pk_add_f32 v[106:107], v[106:107], v[110:111]
	v_pk_add_f32 v[102:103], v[102:103], v[112:113]
	v_lshlrev_b32_e32 v110, 16, v120
	v_and_b32_e32 v111, 0xffff0000, v120
	v_lshlrev_b32_e32 v112, 16, v121
	v_and_b32_e32 v113, 0xffff0000, v121
	v_pk_add_f32 v[108:109], v[108:109], v[110:111]
	v_pk_add_f32 v[104:105], v[104:105], v[112:113]
	s_waitcnt vmcnt(5)
	v_lshlrev_b32_e32 v110, 16, v122
	v_and_b32_e32 v111, 0xffff0000, v122
	v_lshlrev_b32_e32 v112, 16, v123
	v_and_b32_e32 v113, 0xffff0000, v123
	v_pk_add_f32 v[102:103], v[102:103], v[112:113]
	v_pk_add_f32 v[106:107], v[106:107], v[110:111]
	v_lshlrev_b32_e32 v110, 16, v124
	v_and_b32_e32 v111, 0xffff0000, v124
	v_lshlrev_b32_e32 v112, 16, v125
	v_and_b32_e32 v113, 0xffff0000, v125
	v_pk_add_f32 v[104:105], v[104:105], v[112:113]
	v_pk_add_f32 v[108:109], v[108:109], v[110:111]
	s_waitcnt vmcnt(3)
	v_lshlrev_b32_e32 v110, 16, v126
	v_and_b32_e32 v111, 0xffff0000, v126
	v_lshlrev_b32_e32 v112, 16, v127
	v_and_b32_e32 v113, 0xffff0000, v127
	v_pk_add_f32 v[106:107], v[106:107], v[110:111]
	v_pk_add_f32 v[102:103], v[102:103], v[112:113]
	v_lshlrev_b32_e32 v110, 16, v128
	v_and_b32_e32 v111, 0xffff0000, v128
	v_lshlrev_b32_e32 v112, 16, v129
	v_and_b32_e32 v113, 0xffff0000, v129
	v_pk_add_f32 v[108:109], v[108:109], v[110:111]
	v_pk_add_f32 v[104:105], v[104:105], v[112:113]
	s_waitcnt vmcnt(1)
	v_lshlrev_b32_e32 v110, 16, v156
	v_and_b32_e32 v111, 0xffff0000, v156
	v_lshlrev_b32_e32 v112, 16, v157
	v_and_b32_e32 v113, 0xffff0000, v157
	v_pk_add_f32 v[102:103], v[102:103], v[112:113]
	v_pk_add_f32 v[106:107], v[106:107], v[110:111]
	v_lshlrev_b32_e32 v110, 16, v158
	v_and_b32_e32 v111, 0xffff0000, v158
	v_lshlrev_b32_e32 v112, 16, v159
	v_and_b32_e32 v113, 0xffff0000, v159
	v_pk_add_f32 v[112:113], v[104:105], v[112:113]
	v_pk_add_f32 v[108:109], v[108:109], v[110:111]
	v_cvt_pk_bf16_f32 v105, v102, v103
	v_lshlrev_b64 v[102:103], 12, v[160:161]
	v_cvt_pk_bf16_f32 v104, v106, v107
	v_cvt_pk_bf16_f32 v106, v108, v109
	v_lshl_add_u64 v[108:109], s[40:41], 0, v[102:103]
	v_cvt_pk_bf16_f32 v107, v112, v113
	v_lshl_add_u64 v[108:109], v[146:147], 1, v[108:109]
	global_store_dwordx4 v[108:109], v[104:107], off
	v_lshlrev_b32_e32 v108, 16, v94
	v_and_b32_e32 v109, 0xffff0000, v94
	v_lshlrev_b32_e32 v104, 16, v98
	v_and_b32_e32 v105, 0xffff0000, v98
	v_lshlrev_b32_e32 v98, 16, v99
	v_and_b32_e32 v99, 0xffff0000, v99
	v_pk_add_f32 v[104:105], v[104:105], 0 op_sel_hi:[1,0]
	v_pk_add_f32 v[98:99], v[98:99], 0 op_sel_hi:[1,0]
	v_lshlrev_b32_e32 v106, 16, v100
	v_and_b32_e32 v107, 0xffff0000, v100
	v_lshlrev_b32_e32 v100, 16, v101
	v_and_b32_e32 v101, 0xffff0000, v101
	v_lshlrev_b32_e32 v94, 16, v95
	v_and_b32_e32 v95, 0xffff0000, v95
	v_pk_add_f32 v[106:107], v[106:107], 0 op_sel_hi:[1,0]
	v_pk_add_f32 v[100:101], v[100:101], 0 op_sel_hi:[1,0]
	v_pk_add_f32 v[94:95], v[98:99], v[94:95]
	v_pk_add_f32 v[98:99], v[104:105], v[108:109]
	v_lshlrev_b32_e32 v104, 16, v96
	v_and_b32_e32 v105, 0xffff0000, v96
	v_lshlrev_b32_e32 v96, 16, v97
	v_and_b32_e32 v97, 0xffff0000, v97
	v_pk_add_f32 v[96:97], v[100:101], v[96:97]
	v_pk_add_f32 v[100:101], v[106:107], v[104:105]
	v_lshlrev_b32_e32 v104, 16, v90
	v_and_b32_e32 v105, 0xffff0000, v90
	v_lshlrev_b32_e32 v90, 16, v91
	v_and_b32_e32 v91, 0xffff0000, v91
	v_pk_add_f32 v[90:91], v[94:95], v[90:91]
	v_lshlrev_b32_e32 v94, 16, v92
	v_and_b32_e32 v95, 0xffff0000, v92
	v_lshlrev_b32_e32 v92, 16, v93
	v_and_b32_e32 v93, 0xffff0000, v93
	v_pk_add_f32 v[98:99], v[98:99], v[104:105]
	v_pk_add_f32 v[92:93], v[96:97], v[92:93]
	v_lshlrev_b32_e32 v96, 16, v86
	v_and_b32_e32 v97, 0xffff0000, v86
	v_lshlrev_b32_e32 v86, 16, v87
	v_and_b32_e32 v87, 0xffff0000, v87
	v_pk_add_f32 v[94:95], v[100:101], v[94:95]
	v_pk_add_f32 v[86:87], v[90:91], v[86:87]
	v_pk_add_f32 v[90:91], v[98:99], v[96:97]
	v_lshlrev_b32_e32 v96, 16, v88
	v_and_b32_e32 v97, 0xffff0000, v88
	v_lshlrev_b32_e32 v88, 16, v89
	v_and_b32_e32 v89, 0xffff0000, v89
	v_pk_add_f32 v[88:89], v[92:93], v[88:89]
	v_pk_add_f32 v[92:93], v[94:95], v[96:97]
	v_lshlrev_b32_e32 v94, 16, v82
	v_and_b32_e32 v95, 0xffff0000, v82
	v_lshlrev_b32_e32 v82, 16, v83
	v_and_b32_e32 v83, 0xffff0000, v83
	v_pk_add_f32 v[82:83], v[86:87], v[82:83]
	v_lshlrev_b32_e32 v86, 16, v84
	v_and_b32_e32 v87, 0xffff0000, v84
	v_lshlrev_b32_e32 v84, 16, v85
	v_and_b32_e32 v85, 0xffff0000, v85
	v_pk_add_f32 v[90:91], v[90:91], v[94:95]
	v_pk_add_f32 v[84:85], v[88:89], v[84:85]
	v_lshlrev_b32_e32 v88, 16, v78
	v_and_b32_e32 v89, 0xffff0000, v78
	v_lshlrev_b32_e32 v78, 16, v79
	v_and_b32_e32 v79, 0xffff0000, v79
	v_pk_add_f32 v[86:87], v[92:93], v[86:87]
	v_pk_add_f32 v[78:79], v[82:83], v[78:79]
	v_pk_add_f32 v[82:83], v[90:91], v[88:89]
	v_lshlrev_b32_e32 v88, 16, v80
	v_and_b32_e32 v89, 0xffff0000, v80
	v_lshlrev_b32_e32 v80, 16, v81
	v_and_b32_e32 v81, 0xffff0000, v81
	v_pk_add_f32 v[80:81], v[84:85], v[80:81]
	v_pk_add_f32 v[84:85], v[86:87], v[88:89]
	v_lshlrev_b32_e32 v86, 16, v74
	v_and_b32_e32 v87, 0xffff0000, v74
	v_lshlrev_b32_e32 v74, 16, v75
	v_and_b32_e32 v75, 0xffff0000, v75
	v_pk_add_f32 v[74:75], v[78:79], v[74:75]
	v_lshlrev_b32_e32 v78, 16, v76
	v_and_b32_e32 v79, 0xffff0000, v76
	v_lshlrev_b32_e32 v76, 16, v77
	v_and_b32_e32 v77, 0xffff0000, v77
	v_pk_add_f32 v[78:79], v[84:85], v[78:79]
	s_waitcnt vmcnt(1)
	v_lshlrev_b32_e32 v84, 16, v70
	v_and_b32_e32 v85, 0xffff0000, v70
	v_lshlrev_b32_e32 v70, 16, v71
	v_and_b32_e32 v71, 0xffff0000, v71
	v_pk_add_f32 v[82:83], v[82:83], v[86:87]
	v_pk_add_f32 v[80:81], v[80:81], v[76:77]
	v_pk_add_f32 v[76:77], v[74:75], v[70:71]
	v_lshlrev_b32_e32 v70, 16, v72
	v_and_b32_e32 v71, 0xffff0000, v72
	v_lshlrev_b32_e32 v72, 16, v73
	v_and_b32_e32 v73, 0xffff0000, v73
	v_pk_add_f32 v[74:75], v[82:83], v[84:85]
	v_pk_add_f32 v[72:73], v[80:81], v[72:73]
	v_pk_add_f32 v[70:71], v[78:79], v[70:71]

.LBB0_1505:
	s_add_i32 s1, s7, s1
	s_waitcnt vmcnt(0)
	v_lshrrev_b32_e32 v4, 1, v143
	s_ashr_i32 s7, s1, 31
	v_and_b32_e32 v14, 24, v4
	v_lshrrev_b32_e32 v4, 5, v143
	s_lshr_b32 s7, s7, 26
	v_and_b32_e32 v4, 4, v4
	v_bfe_u32 v5, v143, 2, 2
	s_add_i32 s7, s1, s7
	v_lshlrev_b32_e32 v2, 4, v143
	v_and_b32_e32 v1, 32, v143
	v_bfe_u32 v3, v143, 2, 4
	v_or3_b32 v4, v4, v5, v14
	v_lshrrev_b32_e32 v5, 3, v143
	s_movk_i32 s6, 0x70
	s_ashr_i32 s8, s7, 6
	s_and_b32 s7, s7, 0xffc0
	v_bitop3_b32 v12, v2, v1, 48 bitop3:0x6c
	v_and_b32_e32 v13, 64, v143
	v_and_or_b32 v6, v5, s6, v3
	s_movk_i32 s6, 0x60
	s_sub_i32 s7, s1, s7
	v_or_b32_e32 v1, v12, v13
	v_and_or_b32 v5, v5, s6, v4
	s_bfe_i32 s1, s7, 0x80000
	v_lshrrev_b32_e32 v1, 1, v1
	v_mul_u32_u24_e32 v5, 0x1600, v5
	s_bfe_u32 s1, s1, 0x3000c
	v_or_b32_e32 v5, v5, v1
	s_add_i32 s9, s7, s1
	v_lshlrev_b32_e32 v132, 1, v5
	v_add_u32_e32 v5, 0x2000, v2
	s_bfe_i32 s1, s9, 0x80000
	s_and_b32 s9, s9, 0xf8
	v_lshrrev_b32_e32 v5, 7, v5
	s_movk_i32 s6, 0xf0
	s_sub_i32 s7, s7, s9
	v_and_or_b32 v3, v5, s6, v3
	s_movk_i32 s6, 0xe0
	s_lshl_b32 s8, s8, 3
	s_sext_i32_i16 s10, s1
	s_sext_i32_i8 s7, s7
	v_and_or_b32 v4, v5, s6, v4
	s_lshr_b32 s6, s3, 6
	s_add_i32 s42, s8, s7
	s_ashr_i32 s8, s10, 3
	s_lshr_b32 s0, s3, 8
	s_lshl_b32 s48, s6, 10
	s_lshr_b32 s1, s10, 3
	s_mul_hi_i32 s9, s8, 0x2c0000
	s_mul_i32 s8, s8, 0x2c0000
	v_mul_u32_u24_e32 v16, 0x1600, v3
	s_add_u32 s34, s46, s8
	v_or_b32_e32 v3, v16, v1
	s_addc_u32 s35, s47, s9
	s_add_i32 s49, s48, 0
	v_mul_u32_u24_e32 v15, 0x1600, v6
	v_lshlrev_b32_e32 v134, 1, v3
	v_mul_u32_u24_e32 v3, 0x1600, v4
	s_add_i32 m0, s49, 0x10000
	v_or_b32_e32 v6, v1, v15
	v_or_b32_e32 v1, v3, v1
	v_mov_b32_e32 v253, 0xa100
	global_load_dword v253, v253, s[70:71] sc1
	global_load_lds_dwordx4 v132, s[34:35]
	s_add_i32 m0, s49, 0x12000
	v_lshlrev_b32_e32 v136, 1, v1
	s_add_u32 s8, s34, 0x160000
	global_load_lds_dwordx4 v136, s[34:35]
	s_addc_u32 s9, s35, 0
	s_add_i32 m0, s49, 0x14000
	s_mul_i32 s11, s42, 0x2c0000
	global_load_lds_dwordx4 v132, s[8:9]
	s_add_i32 m0, s49, 0x16000
	s_mul_hi_i32 s7, s42, 0x2c0000
	s_add_u32 s30, s38, s11
	s_addc_u32 s31, s39, s7
	s_add_i32 s50, s49, 0x2000
	v_lshlrev_b32_e32 v130, 1, v6
	global_load_lds_dwordx4 v136, s[8:9]
	s_mov_b32 m0, s49
	s_add_u32 s8, s30, 0x160000
	global_load_lds_dwordx4 v130, s[30:31]
	s_mov_b32 m0, s50
	s_addc_u32 s9, s31, 0
	s_add_i32 s51, s49, 0x4000
	global_load_lds_dwordx4 v134, s[30:31]
	s_mov_b32 m0, s51
	s_add_i32 s52, s49, 0x6000
	global_load_lds_dwordx4 v130, s[8:9]
	s_mov_b32 m0, s52
	v_mov_b32_e32 v133, 0
	global_load_lds_dwordx4 v134, s[8:9]
	v_mov_b32_e32 v137, v133
	v_mov_b32_e32 v131, v133
	v_mov_b32_e32 v135, v133
	s_cmp_eq_u32 s0, 1
	s_mov_b32 s7, 0
	v_lshl_add_u64 v[10:11], s[34:35], 0, v[132:133]
	v_lshl_add_u64 v[6:7], s[34:35], 0, v[136:137]
	s_mov_b32 s53, 0x12000
	s_mov_b32 s54, 0x14000
	s_mov_b32 s55, 0x16000
	v_lshl_add_u64 v[8:9], s[30:31], 0, v[130:131]
	v_lshl_add_u64 v[4:5], s[30:31], 0, v[134:135]
	s_movk_i32 s56, 0x4000
	s_cselect_b64 s[8:9], -1, 0
	s_cmp_lg_u32 s0, 1
	s_movk_i32 s57, 0x6000
	s_cbranch_scc1 .LBB0_1507
	s_barrier
.LBB0_1507:
	s_add_u32 s58, s70, 0x13000
	s_addc_u32 s59, s71, 0
	s_lshl_b32 s6, s6, 5
	s_mov_b64 s[10:11], 0x80
	s_and_b32 s6, s6, 0x60
	s_add_i32 m0, s49, 0x18000
	v_lshl_add_u64 v[10:11], v[10:11], 0, s[10:11]
	s_lshl_b32 s14, s0, 13
	s_lshl_b32 s15, s6, 7
	s_waitcnt vmcnt(2)
	s_barrier
	global_load_lds_dwordx4 v[10:11], off
	v_lshl_add_u64 v[6:7], v[6:7], 0, s[10:11]
	s_add_i32 m0, s49, 0x1a000
	s_add_i32 s60, s49, 0x8000
	s_add_i32 s61, s49, 0xa000
	global_load_lds_dwordx4 v[6:7], off
	v_lshl_add_u64 v[6:7], v[8:9], 0, s[10:11]
	s_mov_b32 m0, s60
	s_add_u32 s12, s34, 0x160080
	global_load_lds_dwordx4 v[6:7], off
	v_lshl_add_u64 v[4:5], v[4:5], 0, s[10:11]
	s_mov_b32 m0, s61
	s_addc_u32 s13, s35, 0
	global_load_lds_dwordx4 v[4:5], off
	s_add_i32 m0, s49, 0x1c000
	v_lshl_add_u64 v[4:5], s[12:13], 0, v[132:133]
	global_load_lds_dwordx4 v[4:5], off
	v_lshl_add_u64 v[4:5], s[12:13], 0, v[136:137]
	s_add_i32 m0, s49, 0x1e000
	v_and_b32_e32 v3, 15, v143
	global_load_lds_dwordx4 v[4:5], off
	v_lshlrev_b32_e32 v4, 1, v14
	v_lshlrev_b32_e32 v5, 2, v143
	v_lshl_or_b32 v1, s0, 6, v3
	v_lshl_or_b32 v3, v3, 6, v4
	v_and_b32_e32 v5, 32, v5
	v_bitop3_b32 v6, v3, s14, v5 bitop3:0xde
	v_lshlrev_b32_e32 v3, 6, v143
	s_movk_i32 s0, 0x3c0
	s_cmpk_lt_u32 s3, 0x100
	v_and_or_b32 v3, v3, s0, v4
	s_cselect_b64 s[12:13], -1, 0
	s_cmpk_lt_i32 s2, 0x80
	v_bitop3_b32 v150, s15, v3, v5 bitop3:0xf6
	s_cselect_b64 s[14:15], -1, 0
	s_ashr_i32 s67, s2, 3
	s_and_b32 s76, s2, 7
	v_readfirstlane_b32 s98, v253
	s_cmp_eq_u32 s98, 0
	s_cbranch_scc0 .Lxs_slow_14
	s_lshr_b32 s99, s2, 6
	s_lshl_b32 s99, s99, 3
	s_and_b32 s100, s2, 7
	s_or_b32 s67, s99, s100
	s_bfe_u32 s76, s2, 0x30003
.Lxs_slow_14:
	s_ashr_i32 s2, s2, 6
	v_readlane_b32 s16, v242, 53
	s_add_i32 s77, s2, 32
	s_mul_i32 s2, s76, 10
	v_mov_b32_e32 v3, v133
	v_readlane_b32 s17, v242, 54
	s_and_b32 s78, s67, 7
	s_add_i32 s2, s2, 8
	s_waitcnt vmcnt(6)
	v_lshl_add_u64 v[138:139], s[16:17], 0, v[2:3]
	s_cmp_lt_u32 s76, 4
	s_mul_i32 s3, s76, 12
	v_add_u16_e32 v2, v12, v13
	s_cselect_b32 s79, 12, 10
	s_cselect_b32 s16, s3, s2
	v_lshrrev_b16_e32 v2, 1, v2
	s_add_i32 s80, 0, 0x10000
	s_add_i32 s81, 0, 0x14000
	s_sext_i32_i8 s43, s1
	s_mov_b32 s62, 0x18000
	s_mov_b32 s63, 0x1a000
	s_mov_b32 s33, 0x8000
	s_mov_b32 s65, 0xa000
	s_mov_b32 s66, 0x1c000
	v_cmp_eq_u32_e64 s[0:1], 0, v143
	v_or_b32_e32 v151, s6, v14
	v_add_lshl_u32 v140, v15, v2, 1
	v_mov_b32_e32 v141, v133
	v_add_lshl_u32 v144, v16, v2, 1
	v_mov_b32_e32 v145, v133
	s_mov_b64 s[2:3], -1
	s_movk_i32 s44, 0x58
	s_mov_b32 s88, -1
	v_add_u32_e32 v152, s80, v150
	v_add_u32_e32 v153, s81, v150
	v_add_u32_e32 v154, 0, v6
	s_mov_b32 s82, 0xc000
	s_mov_b32 s83, 0xe000
	s_mov_b32 s84, 0x80000
	s_mov_b32 s85, 0xa0000
	s_mov_b64 s[18:19], 0x80000
	s_mov_b64 s[20:21], 0x90000
	s_mov_b32 s87, 0x90000
	s_mov_b64 s[22:23], 0xa0000
	s_mov_b64 s[24:25], 0xb0000
	s_mov_b32 s6, 0
	s_barrier
	s_branch .LBB0_1510

.LBB0_1518:
	v_lshl_add_u32 v148, s42, 8, v1
	v_lshl_or_b32 v146, s43, 8, v151
	s_mov_b64 s[30:31], -1
	s_cmp_gt_i32 s88, -1
	v_cvt_pk_bf16_f32 v66, v66, v67
	v_cvt_pk_bf16_f32 v67, v68, v69
	v_cvt_pk_bf16_f32 v68, v126, v127
	v_cvt_pk_bf16_f32 v69, v128, v129
	v_cvt_pk_bf16_f32 v62, v62, v63
	v_cvt_pk_bf16_f32 v63, v64, v65
	v_cvt_pk_bf16_f32 v64, v58, v59
	v_cvt_pk_bf16_f32 v65, v60, v61
	v_cvt_pk_bf16_f32 v58, v122, v123
	v_cvt_pk_bf16_f32 v59, v124, v125
	v_cvt_pk_bf16_f32 v60, v118, v119
	v_cvt_pk_bf16_f32 v61, v120, v121
	v_cvt_pk_bf16_f32 v54, v54, v55
	v_cvt_pk_bf16_f32 v55, v56, v57
	v_cvt_pk_bf16_f32 v56, v50, v51
	v_cvt_pk_bf16_f32 v57, v52, v53
	v_cvt_pk_bf16_f32 v50, v114, v115
	v_cvt_pk_bf16_f32 v51, v116, v117
	v_cvt_pk_bf16_f32 v52, v110, v111
	v_cvt_pk_bf16_f32 v53, v112, v113
	v_cvt_pk_bf16_f32 v46, v46, v47
	v_cvt_pk_bf16_f32 v47, v48, v49
	v_cvt_pk_bf16_f32 v48, v42, v43
	v_cvt_pk_bf16_f32 v49, v44, v45
	v_cvt_pk_bf16_f32 v42, v106, v107
	v_cvt_pk_bf16_f32 v43, v108, v109
	v_cvt_pk_bf16_f32 v44, v102, v103
	v_cvt_pk_bf16_f32 v45, v104, v105
	v_cvt_pk_bf16_f32 v38, v38, v39
	v_cvt_pk_bf16_f32 v39, v40, v41
	v_cvt_pk_bf16_f32 v40, v98, v99
	v_cvt_pk_bf16_f32 v41, v100, v101
	v_cvt_pk_bf16_f32 v34, v34, v35
	v_cvt_pk_bf16_f32 v35, v36, v37
	v_cvt_pk_bf16_f32 v36, v94, v95
	v_cvt_pk_bf16_f32 v37, v96, v97
	v_cvt_pk_bf16_f32 v30, v30, v31
	v_cvt_pk_bf16_f32 v31, v32, v33
	v_cvt_pk_bf16_f32 v32, v26, v27
	v_cvt_pk_bf16_f32 v33, v28, v29
	v_cvt_pk_bf16_f32 v26, v90, v91
	v_cvt_pk_bf16_f32 v27, v92, v93
	v_cvt_pk_bf16_f32 v28, v86, v87
	v_cvt_pk_bf16_f32 v29, v88, v89
	v_cvt_pk_bf16_f32 v22, v22, v23
	v_cvt_pk_bf16_f32 v23, v24, v25
	v_cvt_pk_bf16_f32 v24, v18, v19
	v_cvt_pk_bf16_f32 v25, v20, v21
	v_cvt_pk_bf16_f32 v18, v82, v83
	v_cvt_pk_bf16_f32 v19, v84, v85
	v_cvt_pk_bf16_f32 v20, v78, v79
	v_cvt_pk_bf16_f32 v21, v80, v81
	v_cvt_pk_bf16_f32 v14, v14, v15
	v_cvt_pk_bf16_f32 v15, v16, v17
	v_cvt_pk_bf16_f32 v16, v10, v11
	v_cvt_pk_bf16_f32 v17, v12, v13
	v_cvt_pk_bf16_f32 v10, v74, v75
	v_cvt_pk_bf16_f32 v11, v76, v77
	v_cvt_pk_bf16_f32 v12, v70, v71
	v_cvt_pk_bf16_f32 v13, v72, v73
	s_cbranch_scc0 .LBB0_1532
	s_lshl_b32 s30, s6, 3
	s_add_i32 s34, s30, s88
	s_ashr_i32 s35, s34, 31
	s_lshl_b64 s[34:35], s[34:35], 17
	v_lshl_add_u64 v[74:75], v[138:139], 0, s[34:35]
	s_movk_i32 s17, 0x2000
	v_add_co_u32_e32 v70, vcc, s17, v74
	s_mov_b32 s17, 0x10000
	s_nop 0
	v_addc_co_u32_e32 v71, vcc, 0, v75, vcc
	global_store_dwordx4 v[70:71], v[62:65], off
	v_add_co_u32_e32 v70, vcc, s56, v74
	global_store_dwordx4 v[74:75], v[66:69], off
	s_nop 0
	v_addc_co_u32_e32 v71, vcc, 0, v75, vcc
	global_store_dwordx4 v[70:71], v[58:61], off
	v_add_co_u32_e32 v70, vcc, s57, v74
	v_cvt_pk_bf16_f32 v72, v2, v3
	s_nop 0
	v_addc_co_u32_e32 v71, vcc, 0, v75, vcc
	global_store_dwordx4 v[70:71], v[54:57], off
	v_add_co_u32_e32 v70, vcc, s33, v74
	v_cvt_pk_bf16_f32 v73, v4, v5
	s_nop 0
	v_addc_co_u32_e32 v71, vcc, 0, v75, vcc
	global_store_dwordx4 v[70:71], v[50:53], off
	v_add_co_u32_e32 v70, vcc, s65, v74
	s_nop 1
	v_addc_co_u32_e32 v71, vcc, 0, v75, vcc
	global_store_dwordx4 v[70:71], v[46:49], off
	v_add_co_u32_e32 v70, vcc, s82, v74
	s_nop 1
	v_addc_co_u32_e32 v71, vcc, 0, v75, vcc
	global_store_dwordx4 v[70:71], v[42:45], off
	v_add_co_u32_e32 v70, vcc, s83, v74
	s_nop 1
	v_addc_co_u32_e32 v71, vcc, 0, v75, vcc
	global_store_dwordx4 v[70:71], v[38:41], off
	v_add_co_u32_e32 v70, vcc, s17, v74
	s_nop 1
	v_addc_co_u32_e32 v71, vcc, 0, v75, vcc
	global_store_dwordx4 v[70:71], v[34:37], off
	v_add_co_u32_e32 v70, vcc, s53, v74
	s_nop 1
	v_addc_co_u32_e32 v71, vcc, 0, v75, vcc
	global_store_dwordx4 v[70:71], v[30:33], off
	v_add_co_u32_e32 v70, vcc, s54, v74
	s_nop 1
	v_addc_co_u32_e32 v71, vcc, 0, v75, vcc
	global_store_dwordx4 v[70:71], v[26:29], off
	v_add_co_u32_e32 v70, vcc, s55, v74
	s_nop 1
	v_addc_co_u32_e32 v71, vcc, 0, v75, vcc
	global_store_dwordx4 v[70:71], v[22:25], off
	v_add_co_u32_e32 v70, vcc, s62, v74
	s_nop 1
	v_addc_co_u32_e32 v71, vcc, 0, v75, vcc
	global_store_dwordx4 v[70:71], v[18:21], off
	v_add_co_u32_e32 v70, vcc, s63, v74
	s_nop 1
	v_addc_co_u32_e32 v71, vcc, 0, v75, vcc
	global_store_dwordx4 v[70:71], v[14:17], off
	v_add_co_u32_e32 v70, vcc, s66, v74
	s_nop 1
	v_addc_co_u32_e32 v71, vcc, 0, v75, vcc
	v_add_co_u32_e32 v74, vcc, 0x1e000, v74
	global_store_dwordx4 v[70:71], v[10:13], off
	v_cvt_pk_bf16_f32 v70, v6, v7
	v_cvt_pk_bf16_f32 v71, v8, v9
	v_addc_co_u32_e32 v75, vcc, 0, v75, vcc
	global_store_dwordx4 v[74:75], v[70:73], off
	s_waitcnt vmcnt(0)
	s_waitcnt vmcnt(0)
	s_barrier
	s_and_saveexec_b64 s[34:35], s[0:1]
	s_cbranch_execz .LBB0_1531
	s_lshl_b32 s36, s6, 6
	s_mov_b64 s[42:43], exec
	s_ashr_i32 s37, s36, 31
	s_lshl_b64 s[36:37], s[36:37], 2
	s_cmp_eq_u32 s98, 0
	s_cbranch_scc1 .Lxs_nowb_14
	buffer_wbl2 sc1
.Lxs_nowb_14:
	s_waitcnt vmcnt(0)
	v_mbcnt_lo_u32_b32 v70, s42, 0
	s_add_u32 s36, s58, s36
	v_mbcnt_hi_u32_b32 v70, s43, v70
	s_addc_u32 s37, s59, s37
	v_cmp_eq_u32_e32 vcc, 0, v70
	s_and_saveexec_b64 s[44:45], vcc
	s_cbranch_execz .LBB0_1522
	s_bcnt1_i32_b64 s6, s[42:43]
	v_mov_b32_e32 v70, s6
	global_atomic_add v133, v70, s[36:37]

.LBB0_1531:
	s_or_b64 exec, exec, s[34:35]
	s_ashr_i32 s31, s30, 31
	s_lshl_b64 s[30:31], s[30:31], 17
	s_lshl_b32 s6, s88, 1
	v_lshl_add_u64 v[70:71], v[138:139], 0, s[30:31]
	s_lshl_b64 s[30:31], s[6:7], 13
	v_lshl_add_u64 v[70:71], v[70:71], 0, s[30:31]
	v_add_co_u32_e32 v72, vcc, 0x2000, v70
	s_nop 1
	v_addc_co_u32_e32 v73, vcc, 0, v71, vcc
	s_barrier
	global_load_dwordx4 v[102:105], v[70:71], off sc0
	global_load_dwordx4 v[98:101], v[72:73], off sc0
	v_add_co_u32_e32 v72, vcc, 0x20000, v70
	s_lshl_b32 s6, s88, 5
	s_nop 0
	v_addc_co_u32_e32 v73, vcc, 0, v71, vcc
	v_add_co_u32_e32 v74, vcc, 0x22000, v70
	s_and_b32 s6, s6, 0x7fffff80
	s_nop 0
	v_addc_co_u32_e32 v75, vcc, 0, v71, vcc
	global_load_dwordx4 v[106:109], v[72:73], off sc0
	global_load_dwordx4 v[94:97], v[74:75], off sc0
	v_add_co_u32_e32 v72, vcc, 0x40000, v70
	v_add_u32_e32 v147, s6, v148
	s_nop 0
	v_addc_co_u32_e32 v73, vcc, 0, v71, vcc
	v_add_co_u32_e32 v74, vcc, 0x42000, v70
	s_lshl_b32 s6, s88, 4
	s_nop 0
	v_addc_co_u32_e32 v75, vcc, 0, v71, vcc
	global_load_dwordx4 v[110:113], v[72:73], off sc0
	global_load_dwordx4 v[90:93], v[74:75], off sc0
	v_add_co_u32_e32 v72, vcc, 0x60000, v70
	v_and_or_b32 v160, s6, 48, v147
	s_nop 0
	v_addc_co_u32_e32 v73, vcc, 0, v71, vcc
	v_add_co_u32_e32 v74, vcc, 0x62000, v70
	v_ashrrev_i32_e32 v161, 31, v160
	s_nop 0
	v_addc_co_u32_e32 v75, vcc, 0, v71, vcc
	global_load_dwordx4 v[114:117], v[72:73], off sc0
	global_load_dwordx4 v[86:89], v[74:75], off sc0
	v_add_co_u32_e32 v72, vcc, 0x80000, v70
	v_ashrrev_i32_e32 v147, 31, v146
	s_nop 0
	v_addc_co_u32_e32 v73, vcc, 0, v71, vcc
	v_add_co_u32_e32 v74, vcc, 0x82000, v70
	s_mov_b64 s[30:31], 0
	s_nop 0
	v_addc_co_u32_e32 v75, vcc, 0, v71, vcc
	global_load_dwordx4 v[118:121], v[72:73], off sc0
	global_load_dwordx4 v[82:85], v[74:75], off sc0
	v_add_co_u32_e32 v72, vcc, 0xa0000, v70
	s_waitcnt vmcnt(9)
	v_lshlrev_b32_e32 v162, 16, v102
	v_addc_co_u32_e32 v73, vcc, 0, v71, vcc
	v_add_co_u32_e32 v74, vcc, 0xa2000, v70
	v_and_b32_e32 v163, 0xffff0000, v102
	s_nop 0
	v_addc_co_u32_e32 v75, vcc, 0, v71, vcc
	global_load_dwordx4 v[122:125], v[72:73], off sc0
	global_load_dwordx4 v[78:81], v[74:75], off sc0
	v_add_co_u32_e32 v72, vcc, 0xc0000, v70
	v_lshlrev_b32_e32 v102, 16, v103
	s_nop 0
	v_addc_co_u32_e32 v73, vcc, 0, v71, vcc
	v_add_co_u32_e32 v74, vcc, 0xc2000, v70
	v_and_b32_e32 v103, 0xffff0000, v103
	s_nop 0
	v_addc_co_u32_e32 v75, vcc, 0, v71, vcc
	global_load_dwordx4 v[126:129], v[72:73], off sc0
	s_nop 0
	global_load_dwordx4 v[74:77], v[74:75], off sc0
	v_add_co_u32_e32 v72, vcc, 0xe0000, v70
	v_pk_add_f32 v[162:163], v[162:163], 0 op_sel_hi:[1,0]
	s_nop 0
	v_addc_co_u32_e32 v73, vcc, 0, v71, vcc
	v_add_co_u32_e32 v70, vcc, 0xe2000, v70
	v_pk_add_f32 v[102:103], v[102:103], 0 op_sel_hi:[1,0]
	s_nop 0
	v_addc_co_u32_e32 v71, vcc, 0, v71, vcc
	global_load_dwordx4 v[156:159], v[72:73], off sc0
	s_nop 0
	global_load_dwordx4 v[70:73], v[70:71], off sc0
	v_lshlrev_b32_e32 v164, 16, v104
	v_and_b32_e32 v165, 0xffff0000, v104
	v_lshlrev_b32_e32 v104, 16, v105
	v_and_b32_e32 v105, 0xffff0000, v105
	s_waitcnt vmcnt(13)
	v_lshlrev_b32_e32 v166, 16, v106
	v_and_b32_e32 v167, 0xffff0000, v106
	v_lshlrev_b32_e32 v106, 16, v107
	v_and_b32_e32 v107, 0xffff0000, v107
	v_pk_add_f32 v[164:165], v[164:165], 0 op_sel_hi:[1,0]
	v_pk_add_f32 v[104:105], v[104:105], 0 op_sel_hi:[1,0]
	v_pk_add_f32 v[102:103], v[102:103], v[106:107]
	v_pk_add_f32 v[106:107], v[162:163], v[166:167]
	v_lshlrev_b32_e32 v162, 16, v108
	v_and_b32_e32 v163, 0xffff0000, v108
	v_lshlrev_b32_e32 v108, 16, v109
	v_and_b32_e32 v109, 0xffff0000, v109
	v_pk_add_f32 v[104:105], v[104:105], v[108:109]
	v_pk_add_f32 v[108:109], v[164:165], v[162:163]
	s_waitcnt vmcnt(11)
	v_lshlrev_b32_e32 v162, 16, v110
	v_and_b32_e32 v163, 0xffff0000, v110
	v_lshlrev_b32_e32 v110, 16, v111
	v_and_b32_e32 v111, 0xffff0000, v111
	v_pk_add_f32 v[102:103], v[102:103], v[110:111]
	v_lshlrev_b32_e32 v110, 16, v112
	v_and_b32_e32 v111, 0xffff0000, v112
	v_lshlrev_b32_e32 v112, 16, v113
	v_and_b32_e32 v113, 0xffff0000, v113
	v_pk_add_f32 v[106:107], v[106:107], v[162:163]
	v_pk_add_f32 v[108:109], v[108:109], v[110:111]
	v_pk_add_f32 v[104:105], v[104:105], v[112:113]
	s_waitcnt vmcnt(9)
	v_lshlrev_b32_e32 v110, 16, v114
	v_and_b32_e32 v111, 0xffff0000, v114
	v_lshlrev_b32_e32 v112, 16, v115
	v_and_b32_e32 v113, 0xffff0000, v115
	v_pk_add_f32 v[102:103], v[102:103], v[112:113]
	v_pk_add_f32 v[106:107], v[106:107], v[110:111]
	v_lshlrev_b32_e32 v110, 16, v116
	v_and_b32_e32 v111, 0xffff0000, v116
	v_lshlrev_b32_e32 v112, 16, v117
	v_and_b32_e32 v113, 0xffff0000, v117
	v_pk_add_f32 v[104:105], v[104:105], v[112:113]
	v_pk_add_f32 v[108:109], v[108:109], v[110:111]
	s_waitcnt vmcnt(7)
	v_lshlrev_b32_e32 v110, 16, v118
	v_and_b32_e32 v111, 0xffff0000, v118
	v_lshlrev_b32_e32 v112, 16, v119
	v_and_b32_e32 v113, 0xffff0000, v119
	v_pk_add_f32 v[106:107], v[106:107], v[110:111]
	v_pk_add_f32 v[102:103], v[102:103], v[112:113]
	v_lshlrev_b32_e32 v110, 16, v120
	v_and_b32_e32 v111, 0xffff0000, v120
	v_lshlrev_b32_e32 v112, 16, v121
	v_and_b32_e32 v113, 0xffff0000, v121
	v_pk_add_f32 v[108:109], v[108:109], v[110:111]
	v_pk_add_f32 v[104:105], v[104:105], v[112:113]
	s_waitcnt vmcnt(5)
	v_lshlrev_b32_e32 v110, 16, v122
	v_and_b32_e32 v111, 0xffff0000, v122
	v_lshlrev_b32_e32 v112, 16, v123
	v_and_b32_e32 v113, 0xffff0000, v123
	v_pk_add_f32 v[102:103], v[102:103], v[112:113]
	v_pk_add_f32 v[106:107], v[106:107], v[110:111]
	v_lshlrev_b32_e32 v110, 16, v124
	v_and_b32_e32 v111, 0xffff0000, v124
	v_lshlrev_b32_e32 v112, 16, v125
	v_and_b32_e32 v113, 0xffff0000, v125
	v_pk_add_f32 v[104:105], v[104:105], v[112:113]
	v_pk_add_f32 v[108:109], v[108:109], v[110:111]
	s_waitcnt vmcnt(3)
	v_lshlrev_b32_e32 v110, 16, v126
	v_and_b32_e32 v111, 0xffff0000, v126
	v_lshlrev_b32_e32 v112, 16, v127
	v_and_b32_e32 v113, 0xffff0000, v127
	v_pk_add_f32 v[106:107], v[106:107], v[110:111]
	v_pk_add_f32 v[102:103], v[102:103], v[112:113]
	v_lshlrev_b32_e32 v110, 16, v128
	v_and_b32_e32 v111, 0xffff0000, v128
	v_lshlrev_b32_e32 v112, 16, v129
	v_and_b32_e32 v113, 0xffff0000, v129
	v_pk_add_f32 v[108:109], v[108:109], v[110:111]
	v_pk_add_f32 v[104:105], v[104:105], v[112:113]
	s_waitcnt vmcnt(1)
	v_lshlrev_b32_e32 v110, 16, v156
	v_and_b32_e32 v111, 0xffff0000, v156
	v_lshlrev_b32_e32 v112, 16, v157
	v_and_b32_e32 v113, 0xffff0000, v157
	v_pk_add_f32 v[102:103], v[102:103], v[112:113]
	v_pk_add_f32 v[106:107], v[106:107], v[110:111]
	v_lshlrev_b32_e32 v110, 16, v158
	v_and_b32_e32 v111, 0xffff0000, v158
	v_lshlrev_b32_e32 v112, 16, v159
	v_and_b32_e32 v113, 0xffff0000, v159
	v_pk_add_f32 v[112:113], v[104:105], v[112:113]
	v_pk_add_f32 v[108:109], v[108:109], v[110:111]
	v_cvt_pk_bf16_f32 v105, v102, v103
	v_lshlrev_b64 v[102:103], 12, v[160:161]
	v_cvt_pk_bf16_f32 v104, v106, v107
	v_cvt_pk_bf16_f32 v106, v108, v109
	v_lshl_add_u64 v[108:109], s[40:41], 0, v[102:103]
	v_cvt_pk_bf16_f32 v107, v112, v113
	v_lshl_add_u64 v[108:109], v[146:147], 1, v[108:109]
	global_store_dwordx4 v[108:109], v[104:107], off
	v_lshlrev_b32_e32 v108, 16, v94
	v_and_b32_e32 v109, 0xffff0000, v94
	v_lshlrev_b32_e32 v104, 16, v98
	v_and_b32_e32 v105, 0xffff0000, v98
	v_lshlrev_b32_e32 v98, 16, v99
	v_and_b32_e32 v99, 0xffff0000, v99
	v_pk_add_f32 v[104:105], v[104:105], 0 op_sel_hi:[1,0]
	v_pk_add_f32 v[98:99], v[98:99], 0 op_sel_hi:[1,0]
	v_lshlrev_b32_e32 v106, 16, v100
	v_and_b32_e32 v107, 0xffff0000, v100
	v_lshlrev_b32_e32 v100, 16, v101
	v_and_b32_e32 v101, 0xffff0000, v101
	v_lshlrev_b32_e32 v94, 16, v95
	v_and_b32_e32 v95, 0xffff0000, v95
	v_pk_add_f32 v[106:107], v[106:107], 0 op_sel_hi:[1,0]
	v_pk_add_f32 v[100:101], v[100:101], 0 op_sel_hi:[1,0]
	v_pk_add_f32 v[94:95], v[98:99], v[94:95]
	v_pk_add_f32 v[98:99], v[104:105], v[108:109]
	v_lshlrev_b32_e32 v104, 16, v96
	v_and_b32_e32 v105, 0xffff0000, v96
	v_lshlrev_b32_e32 v96, 16, v97
	v_and_b32_e32 v97, 0xffff0000, v97
	v_pk_add_f32 v[96:97], v[100:101], v[96:97]
	v_pk_add_f32 v[100:101], v[106:107], v[104:105]
	v_lshlrev_b32_e32 v104, 16, v90
	v_and_b32_e32 v105, 0xffff0000, v90
	v_lshlrev_b32_e32 v90, 16, v91
	v_and_b32_e32 v91, 0xffff0000, v91
	v_pk_add_f32 v[90:91], v[94:95], v[90:91]
	v_lshlrev_b32_e32 v94, 16, v92
	v_and_b32_e32 v95, 0xffff0000, v92
	v_lshlrev_b32_e32 v92, 16, v93
	v_and_b32_e32 v93, 0xffff0000, v93
	v_pk_add_f32 v[98:99], v[98:99], v[104:105]
	v_pk_add_f32 v[92:93], v[96:97], v[92:93]
	v_lshlrev_b32_e32 v96, 16, v86
	v_and_b32_e32 v97, 0xffff0000, v86
	v_lshlrev_b32_e32 v86, 16, v87
	v_and_b32_e32 v87, 0xffff0000, v87
	v_pk_add_f32 v[94:95], v[100:101], v[94:95]
	v_pk_add_f32 v[86:87], v[90:91], v[86:87]
	v_pk_add_f32 v[90:91], v[98:99], v[96:97]
	v_lshlrev_b32_e32 v96, 16, v88
	v_and_b32_e32 v97, 0xffff0000, v88
	v_lshlrev_b32_e32 v88, 16, v89
	v_and_b32_e32 v89, 0xffff0000, v89
	v_pk_add_f32 v[88:89], v[92:93], v[88:89]
	v_pk_add_f32 v[92:93], v[94:95], v[96:97]
	v_lshlrev_b32_e32 v94, 16, v82
	v_and_b32_e32 v95, 0xffff0000, v82
	v_lshlrev_b32_e32 v82, 16, v83
	v_and_b32_e32 v83, 0xffff0000, v83
	v_pk_add_f32 v[82:83], v[86:87], v[82:83]
	v_lshlrev_b32_e32 v86, 16, v84
	v_and_b32_e32 v87, 0xffff0000, v84
	v_lshlrev_b32_e32 v84, 16, v85
	v_and_b32_e32 v85, 0xffff0000, v85
	v_pk_add_f32 v[90:91], v[90:91], v[94:95]
	v_pk_add_f32 v[84:85], v[88:89], v[84:85]
	v_lshlrev_b32_e32 v88, 16, v78
	v_and_b32_e32 v89, 0xffff0000, v78
	v_lshlrev_b32_e32 v78, 16, v79
	v_and_b32_e32 v79, 0xffff0000, v79
	v_pk_add_f32 v[86:87], v[92:93], v[86:87]
	v_pk_add_f32 v[78:79], v[82:83], v[78:79]
	v_pk_add_f32 v[82:83], v[90:91], v[88:89]
	v_lshlrev_b32_e32 v88, 16, v80
	v_and_b32_e32 v89, 0xffff0000, v80
	v_lshlrev_b32_e32 v80, 16, v81
	v_and_b32_e32 v81, 0xffff0000, v81
	v_pk_add_f32 v[80:81], v[84:85], v[80:81]
	v_pk_add_f32 v[84:85], v[86:87], v[88:89]
	v_lshlrev_b32_e32 v86, 16, v74
	v_and_b32_e32 v87, 0xffff0000, v74
	v_lshlrev_b32_e32 v74, 16, v75
	v_and_b32_e32 v75, 0xffff0000, v75
	v_pk_add_f32 v[74:75], v[78:79], v[74:75]
	v_lshlrev_b32_e32 v78, 16, v76
	v_and_b32_e32 v79, 0xffff0000, v76
	v_lshlrev_b32_e32 v76, 16, v77
	v_and_b32_e32 v77, 0xffff0000, v77
	v_pk_add_f32 v[78:79], v[84:85], v[78:79]
	s_waitcnt vmcnt(1)
	v_lshlrev_b32_e32 v84, 16, v70
	v_and_b32_e32 v85, 0xffff0000, v70
	v_lshlrev_b32_e32 v70, 16, v71
	v_and_b32_e32 v71, 0xffff0000, v71
	v_pk_add_f32 v[82:83], v[82:83], v[86:87]
	v_pk_add_f32 v[80:81], v[80:81], v[76:77]
	v_pk_add_f32 v[76:77], v[74:75], v[70:71]
	v_lshlrev_b32_e32 v70, 16, v72
	v_and_b32_e32 v71, 0xffff0000, v72
	v_lshlrev_b32_e32 v72, 16, v73
	v_and_b32_e32 v73, 0xffff0000, v73
	v_pk_add_f32 v[74:75], v[82:83], v[84:85]
	v_pk_add_f32 v[72:73], v[80:81], v[72:73]
	v_pk_add_f32 v[70:71], v[78:79], v[70:71]
